# add flagged relaxed vmcnt(16) at phase 4 of first K-iteration after a GEMM epilogue + vmcnt(10) at phase 6
# baseline (speedup 1.0000x reference)
.LBB0_450:
	ds_read_b128 v[118:121], v197
	ds_read_b128 v[126:129], v197 offset:1024
	ds_read_b128 v[130:133], v197 offset:2048
	ds_read_b128 v[138:141], v197 offset:3072
	s_add_i32 s10, s7, 0xfffa0080
	s_cmp_eq_u32 s17, 12
	s_cselect_b32 s87, s6, s10
	s_cselect_b32 s86, s72, s16
	s_or_b32 s88, s87, 0x80
	s_add_i32 s10, s7, 0xfffe0000
	s_mov_b32 m0, s41
	ds_read_b128 v[146:149], v198
	ds_read_b128 v[150:153], v198 offset:1024
	ds_read_b128 v[154:157], v198 offset:2048
	ds_read_b128 v[158:161], v198 offset:3072
	ds_read_b128 v[162:165], v198 offset:4096
	ds_read_b128 v[166:169], v198 offset:5120
	ds_read_b128 v[170:173], v198 offset:6144
	ds_read_b128 v[174:177], v198 offset:7168
	buffer_load_dwordx4 v1, s[48:51], s10 offen lds
	s_mov_b32 m0, s42
	s_nop 0
	buffer_load_dwordx4 v1, s[48:51], s7 offen lds
	s_waitcnt lgkmcnt(8)
	s_barrier
	s_waitcnt lgkmcnt(0)
	s_setprio 1
	s_waitcnt lgkmcnt(7)
	v_mfma_f32_16x16x32_bf16 v[142:145], v[118:121], v[146:149], v[142:145]
	v_mfma_f32_16x16x32_bf16 v[134:137], v[130:133], v[146:149], v[134:137]
	s_waitcnt lgkmcnt(5)
	v_mfma_f32_16x16x32_bf16 v[122:125], v[118:121], v[154:157], v[122:125]
	v_mfma_f32_16x16x32_bf16 v[114:117], v[130:133], v[154:157], v[114:117]
	s_waitcnt lgkmcnt(3)
	v_mfma_f32_16x16x32_bf16 v[94:97], v[118:121], v[162:165], v[94:97]
	v_mfma_f32_16x16x32_bf16 v[90:93], v[130:133], v[162:165], v[90:93]
	s_waitcnt lgkmcnt(1)
	v_mfma_f32_16x16x32_bf16 v[82:85], v[118:121], v[170:173], v[82:85]
	v_mfma_f32_16x16x32_bf16 v[74:77], v[130:133], v[170:173], v[74:77]
	v_mfma_f32_16x16x32_bf16 v[142:145], v[126:129], v[150:153], v[142:145]
	v_mfma_f32_16x16x32_bf16 v[134:137], v[138:141], v[150:153], v[134:137]
	v_mfma_f32_16x16x32_bf16 v[122:125], v[126:129], v[158:161], v[122:125]
	v_mfma_f32_16x16x32_bf16 v[114:117], v[138:141], v[158:161], v[114:117]
	v_mfma_f32_16x16x32_bf16 v[94:97], v[126:129], v[166:169], v[94:97]
	v_mfma_f32_16x16x32_bf16 v[90:93], v[138:141], v[166:169], v[90:93]
	s_waitcnt lgkmcnt(0)
	v_mfma_f32_16x16x32_bf16 v[82:85], v[126:129], v[174:177], v[82:85]
	v_mfma_f32_16x16x32_bf16 v[74:77], v[138:141], v[174:177], v[74:77]
	s_setprio 0
	s_barrier
	s_mov_b32 m0, s21
	s_mov_b32 s10, s50
	s_mov_b32 s11, s51
	ds_read_b128 v[178:181], v199
	ds_read_b128 v[182:185], v199 offset:1024
	ds_read_b128 v[190:193], v199 offset:2048
	ds_read_b128 v[202:205], v199 offset:3072
	buffer_load_dwordx4 v194, s[8:11], s86 offen lds
	s_add_i32 s33, s86, 0x20000
	s_mov_b32 m0, s22
	s_nop 0
	buffer_load_dwordx4 v194, s[8:11], s33 offen lds
	s_barrier
	s_waitcnt lgkmcnt(0)
	s_setprio 1
	s_waitcnt lgkmcnt(3)
	v_mfma_f32_16x16x32_bf16 v[110:113], v[178:181], v[146:149], v[110:113]
	s_waitcnt lgkmcnt(1)
	v_mfma_f32_16x16x32_bf16 v[106:109], v[190:193], v[146:149], v[106:109]
	v_mfma_f32_16x16x32_bf16 v[102:105], v[178:181], v[154:157], v[102:105]
	v_mfma_f32_16x16x32_bf16 v[98:101], v[190:193], v[154:157], v[98:101]
	v_mfma_f32_16x16x32_bf16 v[86:89], v[178:181], v[162:165], v[86:89]
	v_mfma_f32_16x16x32_bf16 v[78:81], v[190:193], v[162:165], v[78:81]
	v_mfma_f32_16x16x32_bf16 v[70:73], v[178:181], v[170:173], v[70:73]
	v_mfma_f32_16x16x32_bf16 v[66:69], v[190:193], v[170:173], v[66:69]
	v_mfma_f32_16x16x32_bf16 v[110:113], v[182:185], v[150:153], v[110:113]
	s_waitcnt lgkmcnt(0)
	v_mfma_f32_16x16x32_bf16 v[106:109], v[202:205], v[150:153], v[106:109]
	v_mfma_f32_16x16x32_bf16 v[102:105], v[182:185], v[158:161], v[102:105]
	v_mfma_f32_16x16x32_bf16 v[98:101], v[202:205], v[158:161], v[98:101]
	v_mfma_f32_16x16x32_bf16 v[86:89], v[182:185], v[166:169], v[86:89]
	v_mfma_f32_16x16x32_bf16 v[78:81], v[202:205], v[166:169], v[78:81]
	v_mfma_f32_16x16x32_bf16 v[70:73], v[182:185], v[174:177], v[70:73]
	v_mfma_f32_16x16x32_bf16 v[66:69], v[202:205], v[174:177], v[66:69]
	s_setprio 0
	s_mov_b32 m0, s20
	s_barrier
	ds_read_b128 v[146:149], v198 offset:16384
	ds_read_b128 v[150:153], v198 offset:17408
	ds_read_b128 v[154:157], v198 offset:18432
	ds_read_b128 v[158:161], v198 offset:19456
	ds_read_b128 v[162:165], v198 offset:20480
	ds_read_b128 v[166:169], v198 offset:21504
	ds_read_b128 v[170:173], v198 offset:22528
	ds_read_b128 v[174:177], v198 offset:23552
	buffer_load_dwordx4 v1, s[48:51], s87 offen lds
	s_add_i32 s33, s87, 0x20000
	s_mov_b32 m0, s23
	s_nop 0
	buffer_load_dwordx4 v1, s[48:51], s33 offen lds
	s_barrier
	s_waitcnt lgkmcnt(0)
	s_setprio 1
	s_waitcnt lgkmcnt(7)
	v_mfma_f32_16x16x32_bf16 v[62:65], v[118:121], v[146:149], v[62:65]
	v_mfma_f32_16x16x32_bf16 v[58:61], v[130:133], v[146:149], v[58:61]
	s_waitcnt lgkmcnt(5)
	v_mfma_f32_16x16x32_bf16 v[50:53], v[118:121], v[154:157], v[50:53]
	v_mfma_f32_16x16x32_bf16 v[42:45], v[130:133], v[154:157], v[42:45]
	s_waitcnt lgkmcnt(3)
	v_mfma_f32_16x16x32_bf16 v[34:37], v[118:121], v[162:165], v[34:37]
	v_mfma_f32_16x16x32_bf16 v[26:29], v[130:133], v[162:165], v[26:29]
	s_waitcnt lgkmcnt(1)
	v_mfma_f32_16x16x32_bf16 v[18:21], v[118:121], v[170:173], v[18:21]
	v_mfma_f32_16x16x32_bf16 v[10:13], v[130:133], v[170:173], v[10:13]
	v_mfma_f32_16x16x32_bf16 v[62:65], v[126:129], v[150:153], v[62:65]
	v_mfma_f32_16x16x32_bf16 v[58:61], v[138:141], v[150:153], v[58:61]
	v_mfma_f32_16x16x32_bf16 v[50:53], v[126:129], v[158:161], v[50:53]
	v_mfma_f32_16x16x32_bf16 v[42:45], v[138:141], v[158:161], v[42:45]
	v_mfma_f32_16x16x32_bf16 v[34:37], v[126:129], v[166:169], v[34:37]
	v_mfma_f32_16x16x32_bf16 v[26:29], v[138:141], v[166:169], v[26:29]
	s_waitcnt lgkmcnt(0)
	v_mfma_f32_16x16x32_bf16 v[18:21], v[126:129], v[174:177], v[18:21]
	v_mfma_f32_16x16x32_bf16 v[10:13], v[138:141], v[174:177], v[10:13]
	s_setprio 0
	s_barrier
	s_mov_b32 m0, s24
	s_add_i32 s33, s86, 0x40000
	buffer_load_dwordx4 v194, s[8:11], s33 offen lds
	s_add_i32 s33, s86, 0x60000
	s_mov_b32 m0, s25
	s_nop 0
	buffer_load_dwordx4 v194, s[8:11], s33 offen lds
	s_cmp_eq_u32 s100, 0
	s_cbranch_scc1 .Lfw_2_a
	s_waitcnt vmcnt(16)
	s_mov_b32 s100, 0
	s_branch .Lfw_2_b

.LBB0_766:
	v_mov_b32_e32 v218, 0xbd38aa3b
	v_mov_b32_e32 v219, 0xbd38aa3b
	v_mov_b32_e32 v220, 0x44800000
	v_mov_b32_e32 v221, 0x44800000
	v_lshl_add_u32 v222, s49, 8, v187
	v_lshl_or_b32 v224, s47, 7, v188
	s_nop 0
	v_lshl_add_u32 v222, v222, 10, v224
	s_mov_b32 s47, s39
	s_mov_b32 s49, s45
	s_mov_b32 s50, s46
	v_pk_mul_f32 v[226:227], v[174:175], v[218:219]
	v_pk_mul_f32 v[228:229], v[176:177], v[218:219]
	v_pk_mul_f32 v[230:231], v[166:167], v[218:219]
	v_pk_mul_f32 v[232:233], v[168:169], v[218:219]
	v_exp_f32_e32 v226, v226
	v_exp_f32_e32 v227, v227
	v_exp_f32_e32 v228, v228
	v_exp_f32_e32 v229, v229
	v_exp_f32_e32 v230, v230
	v_exp_f32_e32 v231, v231
	v_exp_f32_e32 v232, v232
	v_exp_f32_e32 v233, v233
	v_pk_fma_f32 v[226:227], v[226:227], v[220:221], v[220:221]
	v_pk_fma_f32 v[228:229], v[228:229], v[220:221], v[220:221]
	v_pk_fma_f32 v[230:231], v[230:231], v[220:221], v[220:221]
	v_pk_fma_f32 v[232:233], v[232:233], v[220:221], v[220:221]
	v_rcp_f32_e32 v226, v226
	v_rcp_f32_e32 v227, v227
	v_rcp_f32_e32 v228, v228
	v_rcp_f32_e32 v229, v229
	v_rcp_f32_e32 v230, v230
	v_rcp_f32_e32 v231, v231
	v_rcp_f32_e32 v232, v232
	v_rcp_f32_e32 v233, v233
	v_pk_mul_f32 v[174:175], v[174:175], v[170:171]
	v_pk_mul_f32 v[176:177], v[176:177], v[172:173]
	v_pk_mul_f32 v[166:167], v[166:167], v[162:163]
	v_pk_mul_f32 v[168:169], v[168:169], v[164:165]
	v_pk_mul_f32 v[174:175], v[174:175], v[226:227]
	v_pk_mul_f32 v[176:177], v[176:177], v[228:229]
	v_pk_mul_f32 v[166:167], v[166:167], v[230:231]
	v_pk_mul_f32 v[168:169], v[168:169], v[232:233]
	v_mov_b32_e32 v223, v222
	v_cvt_pk_fp8_f32 v234, v174, v175
	v_cvt_pk_fp8_f32 v235, v166, v167
	v_cvt_pk_fp8_f32 v234, v176, v177 op_sel:[0,0,1]
	v_cvt_pk_fp8_f32 v235, v168, v169 op_sel:[0,0,1]
	s_nop 0
	global_store_dwordx2 v223, v[234:235], s[70:71]
	s_mov_b32 s100, 1
	v_pk_mul_f32 v[226:227], v[158:159], v[218:219]
	v_pk_mul_f32 v[228:229], v[160:161], v[218:219]
	v_pk_mul_f32 v[230:231], v[150:151], v[218:219]
	v_pk_mul_f32 v[232:233], v[152:153], v[218:219]
	v_exp_f32_e32 v226, v226
	v_exp_f32_e32 v227, v227
	v_exp_f32_e32 v228, v228
	v_exp_f32_e32 v229, v229
	v_exp_f32_e32 v230, v230
	v_exp_f32_e32 v231, v231
	v_exp_f32_e32 v232, v232
	v_exp_f32_e32 v233, v233
	v_pk_fma_f32 v[226:227], v[226:227], v[220:221], v[220:221]
	v_pk_fma_f32 v[228:229], v[228:229], v[220:221], v[220:221]
	v_pk_fma_f32 v[230:231], v[230:231], v[220:221], v[220:221]
	v_pk_fma_f32 v[232:233], v[232:233], v[220:221], v[220:221]
	v_rcp_f32_e32 v226, v226
	v_rcp_f32_e32 v227, v227
	v_rcp_f32_e32 v228, v228
	v_rcp_f32_e32 v229, v229
	v_rcp_f32_e32 v230, v230
	v_rcp_f32_e32 v231, v231
	v_rcp_f32_e32 v232, v232
	v_rcp_f32_e32 v233, v233
	v_pk_mul_f32 v[158:159], v[158:159], v[154:155]
	v_pk_mul_f32 v[160:161], v[160:161], v[156:157]
	v_pk_mul_f32 v[150:151], v[150:151], v[146:147]
	v_pk_mul_f32 v[152:153], v[152:153], v[148:149]
	v_pk_mul_f32 v[158:159], v[158:159], v[226:227]
	v_pk_mul_f32 v[160:161], v[160:161], v[228:229]
	v_pk_mul_f32 v[150:151], v[150:151], v[230:231]
	v_pk_mul_f32 v[152:153], v[152:153], v[232:233]
	v_add_u32_e32 v225, 0x4000, v222
	v_cvt_pk_fp8_f32 v236, v158, v159
	v_cvt_pk_fp8_f32 v237, v150, v151
	v_cvt_pk_fp8_f32 v236, v160, v161 op_sel:[0,0,1]
	v_cvt_pk_fp8_f32 v237, v152, v153 op_sel:[0,0,1]
	s_nop 0
	global_store_dwordx2 v225, v[236:237], s[70:71]
	s_mov_b32 s100, 1
	v_pk_mul_f32 v[226:227], v[142:143], v[218:219]
	v_pk_mul_f32 v[228:229], v[144:145], v[218:219]
	v_pk_mul_f32 v[230:231], v[134:135], v[218:219]
	v_pk_mul_f32 v[232:233], v[136:137], v[218:219]
	v_exp_f32_e32 v226, v226
	v_exp_f32_e32 v227, v227
	v_exp_f32_e32 v228, v228
	v_exp_f32_e32 v229, v229
	v_exp_f32_e32 v230, v230
	v_exp_f32_e32 v231, v231
	v_exp_f32_e32 v232, v232
	v_exp_f32_e32 v233, v233
	v_pk_fma_f32 v[226:227], v[226:227], v[220:221], v[220:221]
	v_pk_fma_f32 v[228:229], v[228:229], v[220:221], v[220:221]
	v_pk_fma_f32 v[230:231], v[230:231], v[220:221], v[220:221]
	v_pk_fma_f32 v[232:233], v[232:233], v[220:221], v[220:221]
	v_rcp_f32_e32 v226, v226
	v_rcp_f32_e32 v227, v227
	v_rcp_f32_e32 v228, v228
	v_rcp_f32_e32 v229, v229
	v_rcp_f32_e32 v230, v230
	v_rcp_f32_e32 v231, v231
	v_rcp_f32_e32 v232, v232
	v_rcp_f32_e32 v233, v233
	v_pk_mul_f32 v[142:143], v[142:143], v[138:139]
	v_pk_mul_f32 v[144:145], v[144:145], v[140:141]
	v_pk_mul_f32 v[134:135], v[134:135], v[130:131]
	v_pk_mul_f32 v[136:137], v[136:137], v[132:133]
	v_pk_mul_f32 v[142:143], v[142:143], v[226:227]
	v_pk_mul_f32 v[144:145], v[144:145], v[228:229]
	v_pk_mul_f32 v[134:135], v[134:135], v[230:231]
	v_pk_mul_f32 v[136:137], v[136:137], v[232:233]
	v_add_u32_e32 v223, 0x8000, v222
	v_cvt_pk_fp8_f32 v234, v142, v143
	v_cvt_pk_fp8_f32 v235, v134, v135
	v_cvt_pk_fp8_f32 v234, v144, v145 op_sel:[0,0,1]
	v_cvt_pk_fp8_f32 v235, v136, v137 op_sel:[0,0,1]
	s_nop 0
	global_store_dwordx2 v223, v[234:235], s[70:71]
	s_mov_b32 s100, 1
	v_pk_mul_f32 v[226:227], v[126:127], v[218:219]
	v_pk_mul_f32 v[228:229], v[128:129], v[218:219]
	v_pk_mul_f32 v[230:231], v[118:119], v[218:219]
	v_pk_mul_f32 v[232:233], v[120:121], v[218:219]
	v_exp_f32_e32 v226, v226
	v_exp_f32_e32 v227, v227
	v_exp_f32_e32 v228, v228
	v_exp_f32_e32 v229, v229
	v_exp_f32_e32 v230, v230
	v_exp_f32_e32 v231, v231
	v_exp_f32_e32 v232, v232
	v_exp_f32_e32 v233, v233
	v_pk_fma_f32 v[226:227], v[226:227], v[220:221], v[220:221]
	v_pk_fma_f32 v[228:229], v[228:229], v[220:221], v[220:221]
	v_pk_fma_f32 v[230:231], v[230:231], v[220:221], v[220:221]
	v_pk_fma_f32 v[232:233], v[232:233], v[220:221], v[220:221]
	v_rcp_f32_e32 v226, v226
	v_rcp_f32_e32 v227, v227
	v_rcp_f32_e32 v228, v228
	v_rcp_f32_e32 v229, v229
	v_rcp_f32_e32 v230, v230
	v_rcp_f32_e32 v231, v231
	v_rcp_f32_e32 v232, v232
	v_rcp_f32_e32 v233, v233
	v_pk_mul_f32 v[126:127], v[126:127], v[122:123]
	v_pk_mul_f32 v[128:129], v[128:129], v[124:125]
	v_pk_mul_f32 v[118:119], v[118:119], v[114:115]
	v_pk_mul_f32 v[120:121], v[120:121], v[116:117]
	v_pk_mul_f32 v[126:127], v[126:127], v[226:227]
	v_pk_mul_f32 v[128:129], v[128:129], v[228:229]
	v_pk_mul_f32 v[118:119], v[118:119], v[230:231]
	v_pk_mul_f32 v[120:121], v[120:121], v[232:233]
	v_add_u32_e32 v225, 0xc000, v222
	v_cvt_pk_fp8_f32 v236, v126, v127
	v_cvt_pk_fp8_f32 v237, v118, v119
	v_cvt_pk_fp8_f32 v236, v128, v129 op_sel:[0,0,1]
	v_cvt_pk_fp8_f32 v237, v120, v121 op_sel:[0,0,1]
	s_nop 0
	global_store_dwordx2 v225, v[236:237], s[70:71]
	s_mov_b32 s100, 1
	v_pk_mul_f32 v[226:227], v[110:111], v[218:219]
	v_pk_mul_f32 v[228:229], v[112:113], v[218:219]
	v_pk_mul_f32 v[230:231], v[102:103], v[218:219]
	v_pk_mul_f32 v[232:233], v[104:105], v[218:219]
	v_exp_f32_e32 v226, v226
	v_exp_f32_e32 v227, v227
	v_exp_f32_e32 v228, v228
	v_exp_f32_e32 v229, v229
	v_exp_f32_e32 v230, v230
	v_exp_f32_e32 v231, v231
	v_exp_f32_e32 v232, v232
	v_exp_f32_e32 v233, v233
	v_pk_fma_f32 v[226:227], v[226:227], v[220:221], v[220:221]
	v_pk_fma_f32 v[228:229], v[228:229], v[220:221], v[220:221]
	v_pk_fma_f32 v[230:231], v[230:231], v[220:221], v[220:221]
	v_pk_fma_f32 v[232:233], v[232:233], v[220:221], v[220:221]
	v_rcp_f32_e32 v226, v226
	v_rcp_f32_e32 v227, v227
	v_rcp_f32_e32 v228, v228
	v_rcp_f32_e32 v229, v229
	v_rcp_f32_e32 v230, v230
	v_rcp_f32_e32 v231, v231
	v_rcp_f32_e32 v232, v232
	v_rcp_f32_e32 v233, v233
	v_pk_mul_f32 v[110:111], v[110:111], v[106:107]
	v_pk_mul_f32 v[112:113], v[112:113], v[108:109]
	v_pk_mul_f32 v[102:103], v[102:103], v[98:99]
	v_pk_mul_f32 v[104:105], v[104:105], v[100:101]
	v_pk_mul_f32 v[110:111], v[110:111], v[226:227]
	v_pk_mul_f32 v[112:113], v[112:113], v[228:229]
	v_pk_mul_f32 v[102:103], v[102:103], v[230:231]
	v_pk_mul_f32 v[104:105], v[104:105], v[232:233]
	v_add_u32_e32 v223, 0x20000, v222
	v_cvt_pk_fp8_f32 v234, v110, v111
	v_cvt_pk_fp8_f32 v235, v102, v103
	v_cvt_pk_fp8_f32 v234, v112, v113 op_sel:[0,0,1]
	v_cvt_pk_fp8_f32 v235, v104, v105 op_sel:[0,0,1]
	s_nop 0
	global_store_dwordx2 v223, v[234:235], s[70:71]
	s_mov_b32 s100, 1
	v_pk_mul_f32 v[226:227], v[94:95], v[218:219]
	v_pk_mul_f32 v[228:229], v[96:97], v[218:219]
	v_pk_mul_f32 v[230:231], v[86:87], v[218:219]
	v_pk_mul_f32 v[232:233], v[88:89], v[218:219]
	v_exp_f32_e32 v226, v226
	v_exp_f32_e32 v227, v227
	v_exp_f32_e32 v228, v228
	v_exp_f32_e32 v229, v229
	v_exp_f32_e32 v230, v230
	v_exp_f32_e32 v231, v231
	v_exp_f32_e32 v232, v232
	v_exp_f32_e32 v233, v233
	v_pk_fma_f32 v[226:227], v[226:227], v[220:221], v[220:221]
	v_pk_fma_f32 v[228:229], v[228:229], v[220:221], v[220:221]
	v_pk_fma_f32 v[230:231], v[230:231], v[220:221], v[220:221]
	v_pk_fma_f32 v[232:233], v[232:233], v[220:221], v[220:221]
	v_rcp_f32_e32 v226, v226
	v_rcp_f32_e32 v227, v227
	v_rcp_f32_e32 v228, v228
	v_rcp_f32_e32 v229, v229
	v_rcp_f32_e32 v230, v230
	v_rcp_f32_e32 v231, v231
	v_rcp_f32_e32 v232, v232
	v_rcp_f32_e32 v233, v233
	v_pk_mul_f32 v[94:95], v[94:95], v[90:91]
	v_pk_mul_f32 v[96:97], v[96:97], v[92:93]
	v_pk_mul_f32 v[86:87], v[86:87], v[82:83]
	v_pk_mul_f32 v[88:89], v[88:89], v[84:85]
	v_pk_mul_f32 v[94:95], v[94:95], v[226:227]
	v_pk_mul_f32 v[96:97], v[96:97], v[228:229]
	v_pk_mul_f32 v[86:87], v[86:87], v[230:231]
	v_pk_mul_f32 v[88:89], v[88:89], v[232:233]
	v_add_u32_e32 v225, 0x24000, v222
	v_cvt_pk_fp8_f32 v236, v94, v95
	v_cvt_pk_fp8_f32 v237, v86, v87
	v_cvt_pk_fp8_f32 v236, v96, v97 op_sel:[0,0,1]
	v_cvt_pk_fp8_f32 v237, v88, v89 op_sel:[0,0,1]
	s_nop 0
	global_store_dwordx2 v225, v[236:237], s[70:71]
	s_mov_b32 s100, 1
	v_pk_mul_f32 v[226:227], v[78:79], v[218:219]
	v_pk_mul_f32 v[228:229], v[80:81], v[218:219]
	v_pk_mul_f32 v[230:231], v[70:71], v[218:219]
	v_pk_mul_f32 v[232:233], v[72:73], v[218:219]
	v_exp_f32_e32 v226, v226
	v_exp_f32_e32 v227, v227
	v_exp_f32_e32 v228, v228
	v_exp_f32_e32 v229, v229
	v_exp_f32_e32 v230, v230
	v_exp_f32_e32 v231, v231
	v_exp_f32_e32 v232, v232
	v_exp_f32_e32 v233, v233
	v_pk_fma_f32 v[226:227], v[226:227], v[220:221], v[220:221]
	v_pk_fma_f32 v[228:229], v[228:229], v[220:221], v[220:221]
	v_pk_fma_f32 v[230:231], v[230:231], v[220:221], v[220:221]
	v_pk_fma_f32 v[232:233], v[232:233], v[220:221], v[220:221]
	v_rcp_f32_e32 v226, v226
	v_rcp_f32_e32 v227, v227
	v_rcp_f32_e32 v228, v228
	v_rcp_f32_e32 v229, v229
	v_rcp_f32_e32 v230, v230
	v_rcp_f32_e32 v231, v231
	v_rcp_f32_e32 v232, v232
	v_rcp_f32_e32 v233, v233
	v_pk_mul_f32 v[78:79], v[78:79], v[74:75]
	v_pk_mul_f32 v[80:81], v[80:81], v[76:77]
	v_pk_mul_f32 v[70:71], v[70:71], v[66:67]
	v_pk_mul_f32 v[72:73], v[72:73], v[68:69]
	v_pk_mul_f32 v[78:79], v[78:79], v[226:227]
	v_pk_mul_f32 v[80:81], v[80:81], v[228:229]
	v_pk_mul_f32 v[70:71], v[70:71], v[230:231]
	v_pk_mul_f32 v[72:73], v[72:73], v[232:233]
	v_add_u32_e32 v223, 0x28000, v222
	v_cvt_pk_fp8_f32 v234, v78, v79
	v_cvt_pk_fp8_f32 v235, v70, v71
	v_cvt_pk_fp8_f32 v234, v80, v81 op_sel:[0,0,1]
	v_cvt_pk_fp8_f32 v235, v72, v73 op_sel:[0,0,1]
	s_nop 0
	global_store_dwordx2 v223, v[234:235], s[70:71]
	s_mov_b32 s100, 1
	v_pk_mul_f32 v[226:227], v[62:63], v[218:219]
	v_pk_mul_f32 v[228:229], v[64:65], v[218:219]
	v_pk_mul_f32 v[230:231], v[54:55], v[218:219]
	v_pk_mul_f32 v[232:233], v[56:57], v[218:219]
	v_exp_f32_e32 v226, v226
	v_exp_f32_e32 v227, v227
	v_exp_f32_e32 v228, v228
	v_exp_f32_e32 v229, v229
	v_exp_f32_e32 v230, v230
	v_exp_f32_e32 v231, v231
	v_exp_f32_e32 v232, v232
	v_exp_f32_e32 v233, v233
	v_pk_fma_f32 v[226:227], v[226:227], v[220:221], v[220:221]
	v_pk_fma_f32 v[228:229], v[228:229], v[220:221], v[220:221]
	v_pk_fma_f32 v[230:231], v[230:231], v[220:221], v[220:221]
	v_pk_fma_f32 v[232:233], v[232:233], v[220:221], v[220:221]
	v_rcp_f32_e32 v226, v226
	v_rcp_f32_e32 v227, v227
	v_rcp_f32_e32 v228, v228
	v_rcp_f32_e32 v229, v229
	v_rcp_f32_e32 v230, v230
	v_rcp_f32_e32 v231, v231
	v_rcp_f32_e32 v232, v232
	v_rcp_f32_e32 v233, v233
	v_pk_mul_f32 v[62:63], v[62:63], v[58:59]
	v_pk_mul_f32 v[64:65], v[64:65], v[60:61]
	v_pk_mul_f32 v[54:55], v[54:55], v[50:51]
	v_pk_mul_f32 v[56:57], v[56:57], v[52:53]
	v_pk_mul_f32 v[62:63], v[62:63], v[226:227]
	v_pk_mul_f32 v[64:65], v[64:65], v[228:229]
	v_pk_mul_f32 v[54:55], v[54:55], v[230:231]
	v_pk_mul_f32 v[56:57], v[56:57], v[232:233]
	v_add_u32_e32 v225, 0x2c000, v222
	v_cvt_pk_fp8_f32 v236, v62, v63
	v_cvt_pk_fp8_f32 v237, v54, v55
	v_cvt_pk_fp8_f32 v236, v64, v65 op_sel:[0,0,1]
	v_cvt_pk_fp8_f32 v237, v56, v57 op_sel:[0,0,1]
	s_nop 0
	global_store_dwordx2 v225, v[236:237], s[70:71]
	s_mov_b32 s100, 1
	s_and_b64 vcc, exec, s[4:5]
	s_cbranch_vccnz .LBB0_777

.LBB0_840:
	ds_read_b128 v[142:145], v137
	ds_read_b128 v[146:149], v137 offset:1024
	ds_read_b128 v[150:153], v137 offset:2048
	ds_read_b128 v[154:157], v137 offset:3072
	s_add_i32 s10, s7, 0xfffd0080
	s_cmp_eq_u32 s79, 4
	s_cselect_b32 s87, s6, s10
	s_cselect_b32 s86, s58, s78
	s_or_b32 s88, s87, 0x80
	s_add_i32 s10, s7, 0xffff0000
	s_mov_b32 m0, s39
	ds_read_b128 v[158:161], v138
	ds_read_b128 v[162:165], v138 offset:1024
	ds_read_b128 v[166:169], v138 offset:2048
	ds_read_b128 v[170:173], v138 offset:3072
	ds_read_b128 v[174:177], v138 offset:4096
	ds_read_b128 v[178:181], v138 offset:5120
	ds_read_b128 v[182:185], v138 offset:6144
	ds_read_b128 v[186:189], v138 offset:7168
	buffer_load_dwordx4 v1, s[44:47], s10 offen lds
	s_mov_b32 m0, s41
	s_nop 0
	buffer_load_dwordx4 v1, s[44:47], s7 offen lds
	s_waitcnt lgkmcnt(8)
	s_barrier
	s_waitcnt lgkmcnt(0)
	s_setprio 1
	s_waitcnt lgkmcnt(4)
	v_mfma_f32_16x16x128_f8f6f4 v[114:117], v[142:149], v[166:173], v[114:117]
	v_mfma_f32_16x16x128_f8f6f4 v[106:109], v[150:157], v[166:173], v[106:109]
	s_waitcnt lgkmcnt(2)
	v_mfma_f32_16x16x128_f8f6f4 v[98:101], v[142:149], v[174:181], v[98:101]
	v_mfma_f32_16x16x128_f8f6f4 v[198:201], v[142:149], v[158:165], v[126:129]
	v_mfma_f32_16x16x128_f8f6f4 v[202:205], v[150:157], v[158:165], v[122:125]
	v_mfma_f32_16x16x128_f8f6f4 v[206:209], v[150:157], v[174:181], v[90:93]
	s_waitcnt lgkmcnt(0)
	v_mfma_f32_16x16x128_f8f6f4 v[210:213], v[142:149], v[182:189], v[82:85]
	v_mfma_f32_16x16x128_f8f6f4 v[214:217], v[150:157], v[182:189], v[74:77]
	s_setprio 0
	s_barrier
	s_mov_b32 m0, s23
	s_mov_b32 s10, s46
	s_mov_b32 s11, s47
	ds_read_b128 v[122:125], v139
	ds_read_b128 v[126:129], v139 offset:1024
	ds_read_b128 v[190:193], v139 offset:2048
	ds_read_b128 v[194:197], v139 offset:3072
	buffer_load_dwordx4 v134, s[8:11], s86 offen lds
	s_add_i32 s33, s86, 0x10000
	s_mov_b32 m0, s24
	s_nop 0
	buffer_load_dwordx4 v134, s[8:11], s33 offen lds
	s_barrier
	s_waitcnt lgkmcnt(0)
	s_setprio 1
	s_waitcnt lgkmcnt(2)
	v_mfma_f32_16x16x128_f8f6f4 v[118:121], v[122:129], v[158:165], v[118:121]
	s_waitcnt lgkmcnt(0)
	v_mfma_f32_16x16x128_f8f6f4 v[110:113], v[190:197], v[158:165], v[110:113]
	v_mfma_f32_16x16x128_f8f6f4 v[102:105], v[122:129], v[166:173], v[102:105]
	v_mfma_f32_16x16x128_f8f6f4 v[158:161], v[190:197], v[166:173], v[94:97]
	v_mfma_f32_16x16x128_f8f6f4 v[162:165], v[122:129], v[174:181], v[86:89]
	v_mfma_f32_16x16x128_f8f6f4 v[166:169], v[190:197], v[174:181], v[78:81]
	v_mfma_f32_16x16x128_f8f6f4 v[170:173], v[122:129], v[182:189], v[70:73]
	v_mfma_f32_16x16x128_f8f6f4 v[174:177], v[190:197], v[182:189], v[18:21]
	s_setprio 0
	s_mov_b32 m0, s22
	s_barrier
	ds_read_b128 v[66:69], v138 offset:16384
	s_nop 1
	ds_read_b128 v[70:73], v138 offset:17408
	ds_read_b128 v[74:77], v138 offset:18432
	ds_read_b128 v[78:81], v138 offset:19456
	ds_read_b128 v[82:85], v138 offset:20480
	ds_read_b128 v[86:89], v138 offset:21504
	ds_read_b128 v[90:93], v138 offset:22528
	ds_read_b128 v[94:97], v138 offset:23552
	buffer_load_dwordx4 v1, s[44:47], s87 offen lds
	s_add_i32 s33, s87, 0x10000
	s_mov_b32 m0, s25
	s_nop 0
	buffer_load_dwordx4 v1, s[44:47], s33 offen lds
	s_barrier
	s_waitcnt lgkmcnt(0)
	s_setprio 1
	s_waitcnt lgkmcnt(6)
	v_mfma_f32_16x16x128_f8f6f4 v[62:65], v[142:149], v[66:73], v[62:65]
	v_mfma_f32_16x16x128_f8f6f4 v[58:61], v[150:157], v[66:73], v[58:61]
	s_waitcnt lgkmcnt(4)
	v_mfma_f32_16x16x128_f8f6f4 v[50:53], v[142:149], v[74:81], v[50:53]
	s_waitcnt lgkmcnt(0)
	v_mfma_f32_16x16x128_f8f6f4 v[230:233], v[142:149], v[90:97], v[230:233]
	v_mfma_f32_16x16x128_f8f6f4 v[218:221], v[150:157], v[74:81], v[42:45]
	v_mfma_f32_16x16x128_f8f6f4 v[222:225], v[142:149], v[82:89], v[34:37]
	v_mfma_f32_16x16x128_f8f6f4 v[226:229], v[150:157], v[82:89], v[26:29]
	v_mfma_f32_16x16x128_f8f6f4 v[234:237], v[150:157], v[90:97], v[10:13]
	s_setprio 0
	s_barrier
	s_mov_b32 m0, s26
	s_add_i32 s33, s86, 0x20000
	buffer_load_dwordx4 v134, s[8:11], s33 offen lds
	s_add_i32 s33, s86, 0x30000
	s_mov_b32 m0, s27
	s_nop 0
	buffer_load_dwordx4 v134, s[8:11], s33 offen lds
	s_cmp_eq_u32 s100, 0
	s_cbranch_scc1 .Lfw_4_a
	s_waitcnt vmcnt(16)
	s_mov_b32 s100, 0
	s_branch .Lfw_4_b

.LBB0_1020:
	ds_read_b128 v[134:137], v141
	ds_read_b128 v[146:149], v141 offset:1024
	ds_read_b128 v[150:153], v141 offset:2048
	ds_read_b128 v[154:157], v141 offset:3072
	s_add_i32 s10, s7, 0xfffa0080
	s_cmp_eq_u32 s47, 12
	s_cselect_b32 s50, s6, s10
	s_cselect_b32 s49, s37, s46
	s_or_b32 s51, s50, 0x80
	s_add_i32 s10, s7, 0xfffe0000
	s_mov_b32 m0, s29
	ds_read_b128 v[158:161], v142
	ds_read_b128 v[162:165], v142 offset:1024
	ds_read_b128 v[166:169], v142 offset:2048
	ds_read_b128 v[170:173], v142 offset:3072
	ds_read_b128 v[174:177], v142 offset:4096
	ds_read_b128 v[178:181], v142 offset:5120
	ds_read_b128 v[182:185], v142 offset:6144
	ds_read_b128 v[186:189], v142 offset:7168
	buffer_load_dwordx4 v1, s[40:43], s10 offen lds
	s_mov_b32 m0, s30
	s_nop 0
	buffer_load_dwordx4 v1, s[40:43], s7 offen lds
	s_waitcnt lgkmcnt(8)
	s_barrier
	s_waitcnt lgkmcnt(0)
	s_setprio 1
	s_waitcnt lgkmcnt(7)
	v_mfma_f32_16x16x32_bf16 v[126:129], v[134:137], v[158:161], v[126:129]
	v_mfma_f32_16x16x32_bf16 v[122:125], v[150:153], v[158:161], v[122:125]
	s_waitcnt lgkmcnt(5)
	v_mfma_f32_16x16x32_bf16 v[118:121], v[134:137], v[166:169], v[118:121]
	v_mfma_f32_16x16x32_bf16 v[110:113], v[150:153], v[166:169], v[110:113]
	s_waitcnt lgkmcnt(3)
	v_mfma_f32_16x16x32_bf16 v[102:105], v[134:137], v[174:177], v[102:105]
	v_mfma_f32_16x16x32_bf16 v[94:97], v[150:153], v[174:177], v[94:97]
	s_waitcnt lgkmcnt(1)
	v_mfma_f32_16x16x32_bf16 v[86:89], v[134:137], v[182:185], v[86:89]
	v_mfma_f32_16x16x32_bf16 v[78:81], v[150:153], v[182:185], v[78:81]
	v_mfma_f32_16x16x32_bf16 v[126:129], v[146:149], v[162:165], v[126:129]
	v_mfma_f32_16x16x32_bf16 v[122:125], v[154:157], v[162:165], v[122:125]
	v_mfma_f32_16x16x32_bf16 v[118:121], v[146:149], v[170:173], v[118:121]
	v_mfma_f32_16x16x32_bf16 v[110:113], v[154:157], v[170:173], v[110:113]
	v_mfma_f32_16x16x32_bf16 v[102:105], v[146:149], v[178:181], v[102:105]
	v_mfma_f32_16x16x32_bf16 v[94:97], v[154:157], v[178:181], v[94:97]
	s_waitcnt lgkmcnt(0)
	v_mfma_f32_16x16x32_bf16 v[86:89], v[146:149], v[186:189], v[86:89]
	v_mfma_f32_16x16x32_bf16 v[78:81], v[154:157], v[186:189], v[78:81]
	s_setprio 0
	s_barrier
	s_mov_b32 m0, s15
	s_mov_b32 s10, s42
	s_mov_b32 s11, s43
	ds_read_b128 v[190:193], v143
	ds_read_b128 v[194:197], v143 offset:1024
	ds_read_b128 v[198:201], v143 offset:2048
	ds_read_b128 v[202:205], v143 offset:3072
	buffer_load_dwordx4 v138, s[8:11], s49 offen lds
	s_add_i32 s33, s49, 0x20000
	s_mov_b32 m0, s16
	s_nop 0
	buffer_load_dwordx4 v138, s[8:11], s33 offen lds
	s_barrier
	s_waitcnt lgkmcnt(0)
	s_setprio 1
	s_waitcnt lgkmcnt(3)
	v_mfma_f32_16x16x32_bf16 v[114:117], v[190:193], v[158:161], v[114:117]
	s_waitcnt lgkmcnt(1)
	v_mfma_f32_16x16x32_bf16 v[106:109], v[198:201], v[158:161], v[106:109]
	v_mfma_f32_16x16x32_bf16 v[98:101], v[190:193], v[166:169], v[98:101]
	v_mfma_f32_16x16x32_bf16 v[90:93], v[198:201], v[166:169], v[90:93]
	v_mfma_f32_16x16x32_bf16 v[82:85], v[190:193], v[174:177], v[82:85]
	v_mfma_f32_16x16x32_bf16 v[74:77], v[198:201], v[174:177], v[74:77]
	v_mfma_f32_16x16x32_bf16 v[70:73], v[190:193], v[182:185], v[70:73]
	v_mfma_f32_16x16x32_bf16 v[66:69], v[198:201], v[182:185], v[66:69]
	v_mfma_f32_16x16x32_bf16 v[114:117], v[194:197], v[162:165], v[114:117]
	s_waitcnt lgkmcnt(0)
	v_mfma_f32_16x16x32_bf16 v[106:109], v[202:205], v[162:165], v[106:109]
	v_mfma_f32_16x16x32_bf16 v[98:101], v[194:197], v[170:173], v[98:101]
	v_mfma_f32_16x16x32_bf16 v[90:93], v[202:205], v[170:173], v[90:93]
	v_mfma_f32_16x16x32_bf16 v[82:85], v[194:197], v[178:181], v[82:85]
	v_mfma_f32_16x16x32_bf16 v[74:77], v[202:205], v[178:181], v[74:77]
	v_mfma_f32_16x16x32_bf16 v[70:73], v[194:197], v[186:189], v[70:73]
	v_mfma_f32_16x16x32_bf16 v[66:69], v[202:205], v[186:189], v[66:69]
	s_setprio 0
	s_mov_b32 m0, s14
	s_barrier
	ds_read_b128 v[158:161], v142 offset:16384
	ds_read_b128 v[162:165], v142 offset:17408
	ds_read_b128 v[166:169], v142 offset:18432
	ds_read_b128 v[170:173], v142 offset:19456
	ds_read_b128 v[174:177], v142 offset:20480
	ds_read_b128 v[178:181], v142 offset:21504
	ds_read_b128 v[182:185], v142 offset:22528
	ds_read_b128 v[186:189], v142 offset:23552
	buffer_load_dwordx4 v1, s[40:43], s50 offen lds
	s_add_i32 s33, s50, 0x20000
	s_mov_b32 m0, s17
	s_nop 0
	buffer_load_dwordx4 v1, s[40:43], s33 offen lds
	s_barrier
	s_waitcnt lgkmcnt(0)
	s_setprio 1
	s_waitcnt lgkmcnt(7)
	v_mfma_f32_16x16x32_bf16 v[62:65], v[134:137], v[158:161], v[62:65]
	v_mfma_f32_16x16x32_bf16 v[58:61], v[150:153], v[158:161], v[58:61]
	s_waitcnt lgkmcnt(5)
	v_mfma_f32_16x16x32_bf16 v[54:57], v[134:137], v[166:169], v[54:57]
	v_mfma_f32_16x16x32_bf16 v[46:49], v[150:153], v[166:169], v[46:49]
	s_waitcnt lgkmcnt(3)
	v_mfma_f32_16x16x32_bf16 v[38:41], v[134:137], v[174:177], v[38:41]
	v_mfma_f32_16x16x32_bf16 v[30:33], v[150:153], v[174:177], v[30:33]
	s_waitcnt lgkmcnt(1)
	v_mfma_f32_16x16x32_bf16 v[22:25], v[134:137], v[182:185], v[22:25]
	v_mfma_f32_16x16x32_bf16 v[14:17], v[150:153], v[182:185], v[14:17]
	v_mfma_f32_16x16x32_bf16 v[62:65], v[146:149], v[162:165], v[62:65]
	v_mfma_f32_16x16x32_bf16 v[58:61], v[154:157], v[162:165], v[58:61]
	v_mfma_f32_16x16x32_bf16 v[54:57], v[146:149], v[170:173], v[54:57]
	v_mfma_f32_16x16x32_bf16 v[46:49], v[154:157], v[170:173], v[46:49]
	v_mfma_f32_16x16x32_bf16 v[38:41], v[146:149], v[178:181], v[38:41]
	v_mfma_f32_16x16x32_bf16 v[30:33], v[154:157], v[178:181], v[30:33]
	s_waitcnt lgkmcnt(0)
	v_mfma_f32_16x16x32_bf16 v[22:25], v[146:149], v[186:189], v[22:25]
	v_mfma_f32_16x16x32_bf16 v[14:17], v[154:157], v[186:189], v[14:17]
	s_setprio 0
	s_barrier
	s_mov_b32 m0, s18
	s_add_i32 s33, s49, 0x40000
	buffer_load_dwordx4 v138, s[8:11], s33 offen lds
	s_add_i32 s33, s49, 0x60000
	s_mov_b32 m0, s19
	s_nop 0
	buffer_load_dwordx4 v138, s[8:11], s33 offen lds
	s_cmp_eq_u32 s100, 0
	s_cbranch_scc1 .Lfw_5_a
	s_waitcnt vmcnt(16)
	s_mov_b32 s100, 0
	s_branch .Lfw_5_b

.LBB0_1334:
	ds_read_b128 v[130:133], v195
	ds_read_b128 v[134:137], v195 offset:1024
	ds_read_b128 v[138:141], v195 offset:2048
	ds_read_b128 v[142:145], v195 offset:3072
	s_add_i32 s10, s7, 0xfffa0080
	s_cmp_eq_u32 s13, 12
	s_cselect_b32 s79, s6, s10
	s_cselect_b32 s78, s58, s12
	s_or_b32 s84, s79, 0x80
	s_add_i32 s10, s7, 0xfffe0000
	s_mov_b32 m0, s39
	ds_read_b128 v[146:149], v196
	ds_read_b128 v[150:153], v196 offset:1024
	ds_read_b128 v[154:157], v196 offset:2048
	ds_read_b128 v[158:161], v196 offset:3072
	ds_read_b128 v[162:165], v196 offset:4096
	ds_read_b128 v[166:169], v196 offset:5120
	ds_read_b128 v[170:173], v196 offset:6144
	ds_read_b128 v[174:177], v196 offset:7168
	buffer_load_dwordx4 v1, s[48:51], s10 offen lds
	s_mov_b32 m0, s41
	s_nop 0
	buffer_load_dwordx4 v1, s[48:51], s7 offen lds
	s_waitcnt lgkmcnt(8)
	s_barrier
	s_waitcnt lgkmcnt(0)
	s_setprio 1
	s_waitcnt lgkmcnt(7)
	v_mfma_f32_16x16x32_bf16 v[126:129], v[130:133], v[146:149], v[126:129]
	v_mfma_f32_16x16x32_bf16 v[122:125], v[138:141], v[146:149], v[122:125]
	s_waitcnt lgkmcnt(5)
	v_mfma_f32_16x16x32_bf16 v[110:113], v[130:133], v[154:157], v[110:113]
	v_mfma_f32_16x16x32_bf16 v[106:109], v[138:141], v[154:157], v[106:109]
	s_waitcnt lgkmcnt(3)
	v_mfma_f32_16x16x32_bf16 v[94:97], v[130:133], v[162:165], v[94:97]
	v_mfma_f32_16x16x32_bf16 v[90:93], v[138:141], v[162:165], v[90:93]
	s_waitcnt lgkmcnt(1)
	v_mfma_f32_16x16x32_bf16 v[78:81], v[130:133], v[170:173], v[78:81]
	v_mfma_f32_16x16x32_bf16 v[74:77], v[138:141], v[170:173], v[74:77]
	v_mfma_f32_16x16x32_bf16 v[126:129], v[134:137], v[150:153], v[126:129]
	v_mfma_f32_16x16x32_bf16 v[122:125], v[142:145], v[150:153], v[122:125]
	v_mfma_f32_16x16x32_bf16 v[110:113], v[134:137], v[158:161], v[110:113]
	v_mfma_f32_16x16x32_bf16 v[106:109], v[142:145], v[158:161], v[106:109]
	v_mfma_f32_16x16x32_bf16 v[94:97], v[134:137], v[166:169], v[94:97]
	v_mfma_f32_16x16x32_bf16 v[90:93], v[142:145], v[166:169], v[90:93]
	s_waitcnt lgkmcnt(0)
	v_mfma_f32_16x16x32_bf16 v[78:81], v[134:137], v[174:177], v[78:81]
	v_mfma_f32_16x16x32_bf16 v[74:77], v[142:145], v[174:177], v[74:77]
	s_setprio 0
	s_barrier
	s_mov_b32 m0, s17
	s_mov_b32 s10, s50
	s_mov_b32 s11, s51
	ds_read_b128 v[178:181], v197
	ds_read_b128 v[182:185], v197 offset:1024
	ds_read_b128 v[200:203], v197 offset:2048
	ds_read_b128 v[204:207], v197 offset:3072
	buffer_load_dwordx4 v192, s[8:11], s78 offen lds
	s_add_i32 s33, s78, 0x20000
	s_mov_b32 m0, s18
	s_nop 0
	buffer_load_dwordx4 v192, s[8:11], s33 offen lds
	s_barrier
	s_waitcnt lgkmcnt(0)
	s_setprio 1
	s_waitcnt lgkmcnt(3)
	v_mfma_f32_16x16x32_bf16 v[118:121], v[178:181], v[146:149], v[118:121]
	s_waitcnt lgkmcnt(1)
	v_mfma_f32_16x16x32_bf16 v[114:117], v[200:203], v[146:149], v[114:117]
	v_mfma_f32_16x16x32_bf16 v[102:105], v[178:181], v[154:157], v[102:105]
	v_mfma_f32_16x16x32_bf16 v[98:101], v[200:203], v[154:157], v[98:101]
	v_mfma_f32_16x16x32_bf16 v[86:89], v[178:181], v[162:165], v[86:89]
	v_mfma_f32_16x16x32_bf16 v[82:85], v[200:203], v[162:165], v[82:85]
	v_mfma_f32_16x16x32_bf16 v[70:73], v[178:181], v[170:173], v[70:73]
	v_mfma_f32_16x16x32_bf16 v[66:69], v[200:203], v[170:173], v[66:69]
	v_mfma_f32_16x16x32_bf16 v[118:121], v[182:185], v[150:153], v[118:121]
	s_waitcnt lgkmcnt(0)
	v_mfma_f32_16x16x32_bf16 v[114:117], v[204:207], v[150:153], v[114:117]
	v_mfma_f32_16x16x32_bf16 v[102:105], v[182:185], v[158:161], v[102:105]
	v_mfma_f32_16x16x32_bf16 v[98:101], v[204:207], v[158:161], v[98:101]
	v_mfma_f32_16x16x32_bf16 v[86:89], v[182:185], v[166:169], v[86:89]
	v_mfma_f32_16x16x32_bf16 v[82:85], v[204:207], v[166:169], v[82:85]
	v_mfma_f32_16x16x32_bf16 v[70:73], v[182:185], v[174:177], v[70:73]
	v_mfma_f32_16x16x32_bf16 v[66:69], v[204:207], v[174:177], v[66:69]
	s_setprio 0
	s_mov_b32 m0, s16
	s_barrier
	ds_read_b128 v[146:149], v196 offset:16384
	ds_read_b128 v[150:153], v196 offset:17408
	ds_read_b128 v[154:157], v196 offset:18432
	ds_read_b128 v[158:161], v196 offset:19456
	ds_read_b128 v[162:165], v196 offset:20480
	ds_read_b128 v[166:169], v196 offset:21504
	ds_read_b128 v[170:173], v196 offset:22528
	ds_read_b128 v[174:177], v196 offset:23552
	buffer_load_dwordx4 v1, s[48:51], s79 offen lds
	s_add_i32 s33, s79, 0x20000
	s_mov_b32 m0, s19
	s_nop 0
	buffer_load_dwordx4 v1, s[48:51], s33 offen lds
	s_barrier
	s_waitcnt lgkmcnt(0)
	s_setprio 1
	s_waitcnt lgkmcnt(7)
	v_mfma_f32_16x16x32_bf16 v[62:65], v[130:133], v[146:149], v[62:65]
	v_mfma_f32_16x16x32_bf16 v[58:61], v[138:141], v[146:149], v[58:61]
	s_waitcnt lgkmcnt(5)
	v_mfma_f32_16x16x32_bf16 v[46:49], v[130:133], v[154:157], v[46:49]
	v_mfma_f32_16x16x32_bf16 v[42:45], v[138:141], v[154:157], v[42:45]
	s_waitcnt lgkmcnt(3)
	v_mfma_f32_16x16x32_bf16 v[30:33], v[130:133], v[162:165], v[30:33]
	v_mfma_f32_16x16x32_bf16 v[26:29], v[138:141], v[162:165], v[26:29]
	s_waitcnt lgkmcnt(1)
	v_mfma_f32_16x16x32_bf16 v[14:17], v[130:133], v[170:173], v[14:17]
	v_mfma_f32_16x16x32_bf16 v[10:13], v[138:141], v[170:173], v[10:13]
	v_mfma_f32_16x16x32_bf16 v[62:65], v[134:137], v[150:153], v[62:65]
	v_mfma_f32_16x16x32_bf16 v[58:61], v[142:145], v[150:153], v[58:61]
	v_mfma_f32_16x16x32_bf16 v[46:49], v[134:137], v[158:161], v[46:49]
	v_mfma_f32_16x16x32_bf16 v[42:45], v[142:145], v[158:161], v[42:45]
	v_mfma_f32_16x16x32_bf16 v[30:33], v[134:137], v[166:169], v[30:33]
	v_mfma_f32_16x16x32_bf16 v[26:29], v[142:145], v[166:169], v[26:29]
	s_waitcnt lgkmcnt(0)
	v_mfma_f32_16x16x32_bf16 v[14:17], v[134:137], v[174:177], v[14:17]
	v_mfma_f32_16x16x32_bf16 v[10:13], v[142:145], v[174:177], v[10:13]
	s_setprio 0
	s_barrier
	s_mov_b32 m0, s20
	s_add_i32 s33, s78, 0x40000
	buffer_load_dwordx4 v192, s[8:11], s33 offen lds
	s_add_i32 s33, s78, 0x60000
	s_mov_b32 m0, s21
	s_nop 0
	buffer_load_dwordx4 v192, s[8:11], s33 offen lds
	s_cmp_eq_u32 s100, 0
	s_cbranch_scc1 .Lfw_6_a
	s_waitcnt vmcnt(16)
	s_mov_b32 s100, 0
	s_branch .Lfw_6_b

.LBB0_1650:
	v_mov_b32_e32 v218, 0xbd38aa3b
	v_mov_b32_e32 v219, 0xbd38aa3b
	v_mov_b32_e32 v220, 0x44800000
	v_mov_b32_e32 v221, 0x44800000
	v_lshl_add_u32 v222, s49, 8, v187
	v_lshl_or_b32 v224, s47, 7, v188
	s_nop 0
	v_lshl_add_u32 v222, v222, 10, v224
	s_mov_b32 s47, s39
	s_mov_b32 s49, s45
	s_mov_b32 s57, s46
	v_pk_mul_f32 v[226:227], v[174:175], v[218:219]
	v_pk_mul_f32 v[228:229], v[176:177], v[218:219]
	v_pk_mul_f32 v[230:231], v[166:167], v[218:219]
	v_pk_mul_f32 v[232:233], v[168:169], v[218:219]
	v_exp_f32_e32 v226, v226
	v_exp_f32_e32 v227, v227
	v_exp_f32_e32 v228, v228
	v_exp_f32_e32 v229, v229
	v_exp_f32_e32 v230, v230
	v_exp_f32_e32 v231, v231
	v_exp_f32_e32 v232, v232
	v_exp_f32_e32 v233, v233
	v_pk_fma_f32 v[226:227], v[226:227], v[220:221], v[220:221]
	v_pk_fma_f32 v[228:229], v[228:229], v[220:221], v[220:221]
	v_pk_fma_f32 v[230:231], v[230:231], v[220:221], v[220:221]
	v_pk_fma_f32 v[232:233], v[232:233], v[220:221], v[220:221]
	v_rcp_f32_e32 v226, v226
	v_rcp_f32_e32 v227, v227
	v_rcp_f32_e32 v228, v228
	v_rcp_f32_e32 v229, v229
	v_rcp_f32_e32 v230, v230
	v_rcp_f32_e32 v231, v231
	v_rcp_f32_e32 v232, v232
	v_rcp_f32_e32 v233, v233
	v_pk_mul_f32 v[174:175], v[174:175], v[170:171]
	v_pk_mul_f32 v[176:177], v[176:177], v[172:173]
	v_pk_mul_f32 v[166:167], v[166:167], v[162:163]
	v_pk_mul_f32 v[168:169], v[168:169], v[164:165]
	v_pk_mul_f32 v[174:175], v[174:175], v[226:227]
	v_pk_mul_f32 v[176:177], v[176:177], v[228:229]
	v_pk_mul_f32 v[166:167], v[166:167], v[230:231]
	v_pk_mul_f32 v[168:169], v[168:169], v[232:233]
	v_mov_b32_e32 v223, v222
	v_cvt_pk_fp8_f32 v234, v174, v175
	v_cvt_pk_fp8_f32 v235, v166, v167
	v_cvt_pk_fp8_f32 v234, v176, v177 op_sel:[0,0,1]
	v_cvt_pk_fp8_f32 v235, v168, v169 op_sel:[0,0,1]
	s_nop 0
	global_store_dwordx2 v223, v[234:235], s[70:71]
	s_mov_b32 s100, 1
	v_pk_mul_f32 v[226:227], v[158:159], v[218:219]
	v_pk_mul_f32 v[228:229], v[160:161], v[218:219]
	v_pk_mul_f32 v[230:231], v[150:151], v[218:219]
	v_pk_mul_f32 v[232:233], v[152:153], v[218:219]
	v_exp_f32_e32 v226, v226
	v_exp_f32_e32 v227, v227
	v_exp_f32_e32 v228, v228
	v_exp_f32_e32 v229, v229
	v_exp_f32_e32 v230, v230
	v_exp_f32_e32 v231, v231
	v_exp_f32_e32 v232, v232
	v_exp_f32_e32 v233, v233
	v_pk_fma_f32 v[226:227], v[226:227], v[220:221], v[220:221]
	v_pk_fma_f32 v[228:229], v[228:229], v[220:221], v[220:221]
	v_pk_fma_f32 v[230:231], v[230:231], v[220:221], v[220:221]
	v_pk_fma_f32 v[232:233], v[232:233], v[220:221], v[220:221]
	v_rcp_f32_e32 v226, v226
	v_rcp_f32_e32 v227, v227
	v_rcp_f32_e32 v228, v228
	v_rcp_f32_e32 v229, v229
	v_rcp_f32_e32 v230, v230
	v_rcp_f32_e32 v231, v231
	v_rcp_f32_e32 v232, v232
	v_rcp_f32_e32 v233, v233
	v_pk_mul_f32 v[158:159], v[158:159], v[154:155]
	v_pk_mul_f32 v[160:161], v[160:161], v[156:157]
	v_pk_mul_f32 v[150:151], v[150:151], v[146:147]
	v_pk_mul_f32 v[152:153], v[152:153], v[148:149]
	v_pk_mul_f32 v[158:159], v[158:159], v[226:227]
	v_pk_mul_f32 v[160:161], v[160:161], v[228:229]
	v_pk_mul_f32 v[150:151], v[150:151], v[230:231]
	v_pk_mul_f32 v[152:153], v[152:153], v[232:233]
	v_add_u32_e32 v225, 0x4000, v222
	v_cvt_pk_fp8_f32 v236, v158, v159
	v_cvt_pk_fp8_f32 v237, v150, v151
	v_cvt_pk_fp8_f32 v236, v160, v161 op_sel:[0,0,1]
	v_cvt_pk_fp8_f32 v237, v152, v153 op_sel:[0,0,1]
	s_nop 0
	global_store_dwordx2 v225, v[236:237], s[70:71]
	s_mov_b32 s100, 1
	v_pk_mul_f32 v[226:227], v[142:143], v[218:219]
	v_pk_mul_f32 v[228:229], v[144:145], v[218:219]
	v_pk_mul_f32 v[230:231], v[134:135], v[218:219]
	v_pk_mul_f32 v[232:233], v[136:137], v[218:219]
	v_exp_f32_e32 v226, v226
	v_exp_f32_e32 v227, v227
	v_exp_f32_e32 v228, v228
	v_exp_f32_e32 v229, v229
	v_exp_f32_e32 v230, v230
	v_exp_f32_e32 v231, v231
	v_exp_f32_e32 v232, v232
	v_exp_f32_e32 v233, v233
	v_pk_fma_f32 v[226:227], v[226:227], v[220:221], v[220:221]
	v_pk_fma_f32 v[228:229], v[228:229], v[220:221], v[220:221]
	v_pk_fma_f32 v[230:231], v[230:231], v[220:221], v[220:221]
	v_pk_fma_f32 v[232:233], v[232:233], v[220:221], v[220:221]
	v_rcp_f32_e32 v226, v226
	v_rcp_f32_e32 v227, v227
	v_rcp_f32_e32 v228, v228
	v_rcp_f32_e32 v229, v229
	v_rcp_f32_e32 v230, v230
	v_rcp_f32_e32 v231, v231
	v_rcp_f32_e32 v232, v232
	v_rcp_f32_e32 v233, v233
	v_pk_mul_f32 v[142:143], v[142:143], v[138:139]
	v_pk_mul_f32 v[144:145], v[144:145], v[140:141]
	v_pk_mul_f32 v[134:135], v[134:135], v[130:131]
	v_pk_mul_f32 v[136:137], v[136:137], v[132:133]
	v_pk_mul_f32 v[142:143], v[142:143], v[226:227]
	v_pk_mul_f32 v[144:145], v[144:145], v[228:229]
	v_pk_mul_f32 v[134:135], v[134:135], v[230:231]
	v_pk_mul_f32 v[136:137], v[136:137], v[232:233]
	v_add_u32_e32 v223, 0x8000, v222
	v_cvt_pk_fp8_f32 v234, v142, v143
	v_cvt_pk_fp8_f32 v235, v134, v135
	v_cvt_pk_fp8_f32 v234, v144, v145 op_sel:[0,0,1]
	v_cvt_pk_fp8_f32 v235, v136, v137 op_sel:[0,0,1]
	s_nop 0
	global_store_dwordx2 v223, v[234:235], s[70:71]
	s_mov_b32 s100, 1
	v_pk_mul_f32 v[226:227], v[126:127], v[218:219]
	v_pk_mul_f32 v[228:229], v[128:129], v[218:219]
	v_pk_mul_f32 v[230:231], v[118:119], v[218:219]
	v_pk_mul_f32 v[232:233], v[120:121], v[218:219]
	v_exp_f32_e32 v226, v226
	v_exp_f32_e32 v227, v227
	v_exp_f32_e32 v228, v228
	v_exp_f32_e32 v229, v229
	v_exp_f32_e32 v230, v230
	v_exp_f32_e32 v231, v231
	v_exp_f32_e32 v232, v232
	v_exp_f32_e32 v233, v233
	v_pk_fma_f32 v[226:227], v[226:227], v[220:221], v[220:221]
	v_pk_fma_f32 v[228:229], v[228:229], v[220:221], v[220:221]
	v_pk_fma_f32 v[230:231], v[230:231], v[220:221], v[220:221]
	v_pk_fma_f32 v[232:233], v[232:233], v[220:221], v[220:221]
	v_rcp_f32_e32 v226, v226
	v_rcp_f32_e32 v227, v227
	v_rcp_f32_e32 v228, v228
	v_rcp_f32_e32 v229, v229
	v_rcp_f32_e32 v230, v230
	v_rcp_f32_e32 v231, v231
	v_rcp_f32_e32 v232, v232
	v_rcp_f32_e32 v233, v233
	v_pk_mul_f32 v[126:127], v[126:127], v[122:123]
	v_pk_mul_f32 v[128:129], v[128:129], v[124:125]
	v_pk_mul_f32 v[118:119], v[118:119], v[114:115]
	v_pk_mul_f32 v[120:121], v[120:121], v[116:117]
	v_pk_mul_f32 v[126:127], v[126:127], v[226:227]
	v_pk_mul_f32 v[128:129], v[128:129], v[228:229]
	v_pk_mul_f32 v[118:119], v[118:119], v[230:231]
	v_pk_mul_f32 v[120:121], v[120:121], v[232:233]
	v_add_u32_e32 v225, 0xc000, v222
	v_cvt_pk_fp8_f32 v236, v126, v127
	v_cvt_pk_fp8_f32 v237, v118, v119
	v_cvt_pk_fp8_f32 v236, v128, v129 op_sel:[0,0,1]
	v_cvt_pk_fp8_f32 v237, v120, v121 op_sel:[0,0,1]
	s_nop 0
	global_store_dwordx2 v225, v[236:237], s[70:71]
	s_mov_b32 s100, 1
	v_pk_mul_f32 v[226:227], v[110:111], v[218:219]
	v_pk_mul_f32 v[228:229], v[112:113], v[218:219]
	v_pk_mul_f32 v[230:231], v[102:103], v[218:219]
	v_pk_mul_f32 v[232:233], v[104:105], v[218:219]
	v_exp_f32_e32 v226, v226
	v_exp_f32_e32 v227, v227
	v_exp_f32_e32 v228, v228
	v_exp_f32_e32 v229, v229
	v_exp_f32_e32 v230, v230
	v_exp_f32_e32 v231, v231
	v_exp_f32_e32 v232, v232
	v_exp_f32_e32 v233, v233
	v_pk_fma_f32 v[226:227], v[226:227], v[220:221], v[220:221]
	v_pk_fma_f32 v[228:229], v[228:229], v[220:221], v[220:221]
	v_pk_fma_f32 v[230:231], v[230:231], v[220:221], v[220:221]
	v_pk_fma_f32 v[232:233], v[232:233], v[220:221], v[220:221]
	v_rcp_f32_e32 v226, v226
	v_rcp_f32_e32 v227, v227
	v_rcp_f32_e32 v228, v228
	v_rcp_f32_e32 v229, v229
	v_rcp_f32_e32 v230, v230
	v_rcp_f32_e32 v231, v231
	v_rcp_f32_e32 v232, v232
	v_rcp_f32_e32 v233, v233
	v_pk_mul_f32 v[110:111], v[110:111], v[106:107]
	v_pk_mul_f32 v[112:113], v[112:113], v[108:109]
	v_pk_mul_f32 v[102:103], v[102:103], v[98:99]
	v_pk_mul_f32 v[104:105], v[104:105], v[100:101]
	v_pk_mul_f32 v[110:111], v[110:111], v[226:227]
	v_pk_mul_f32 v[112:113], v[112:113], v[228:229]
	v_pk_mul_f32 v[102:103], v[102:103], v[230:231]
	v_pk_mul_f32 v[104:105], v[104:105], v[232:233]
	v_add_u32_e32 v223, 0x20000, v222
	v_cvt_pk_fp8_f32 v234, v110, v111
	v_cvt_pk_fp8_f32 v235, v102, v103
	v_cvt_pk_fp8_f32 v234, v112, v113 op_sel:[0,0,1]
	v_cvt_pk_fp8_f32 v235, v104, v105 op_sel:[0,0,1]
	s_nop 0
	global_store_dwordx2 v223, v[234:235], s[70:71]
	s_mov_b32 s100, 1
	v_pk_mul_f32 v[226:227], v[94:95], v[218:219]
	v_pk_mul_f32 v[228:229], v[96:97], v[218:219]
	v_pk_mul_f32 v[230:231], v[86:87], v[218:219]
	v_pk_mul_f32 v[232:233], v[88:89], v[218:219]
	v_exp_f32_e32 v226, v226
	v_exp_f32_e32 v227, v227
	v_exp_f32_e32 v228, v228
	v_exp_f32_e32 v229, v229
	v_exp_f32_e32 v230, v230
	v_exp_f32_e32 v231, v231
	v_exp_f32_e32 v232, v232
	v_exp_f32_e32 v233, v233
	v_pk_fma_f32 v[226:227], v[226:227], v[220:221], v[220:221]
	v_pk_fma_f32 v[228:229], v[228:229], v[220:221], v[220:221]
	v_pk_fma_f32 v[230:231], v[230:231], v[220:221], v[220:221]
	v_pk_fma_f32 v[232:233], v[232:233], v[220:221], v[220:221]
	v_rcp_f32_e32 v226, v226
	v_rcp_f32_e32 v227, v227
	v_rcp_f32_e32 v228, v228
	v_rcp_f32_e32 v229, v229
	v_rcp_f32_e32 v230, v230
	v_rcp_f32_e32 v231, v231
	v_rcp_f32_e32 v232, v232
	v_rcp_f32_e32 v233, v233
	v_pk_mul_f32 v[94:95], v[94:95], v[90:91]
	v_pk_mul_f32 v[96:97], v[96:97], v[92:93]
	v_pk_mul_f32 v[86:87], v[86:87], v[82:83]
	v_pk_mul_f32 v[88:89], v[88:89], v[84:85]
	v_pk_mul_f32 v[94:95], v[94:95], v[226:227]
	v_pk_mul_f32 v[96:97], v[96:97], v[228:229]
	v_pk_mul_f32 v[86:87], v[86:87], v[230:231]
	v_pk_mul_f32 v[88:89], v[88:89], v[232:233]
	v_add_u32_e32 v225, 0x24000, v222
	v_cvt_pk_fp8_f32 v236, v94, v95
	v_cvt_pk_fp8_f32 v237, v86, v87
	v_cvt_pk_fp8_f32 v236, v96, v97 op_sel:[0,0,1]
	v_cvt_pk_fp8_f32 v237, v88, v89 op_sel:[0,0,1]
	s_nop 0
	global_store_dwordx2 v225, v[236:237], s[70:71]
	s_mov_b32 s100, 1
	v_pk_mul_f32 v[226:227], v[78:79], v[218:219]
	v_pk_mul_f32 v[228:229], v[80:81], v[218:219]
	v_pk_mul_f32 v[230:231], v[70:71], v[218:219]
	v_pk_mul_f32 v[232:233], v[72:73], v[218:219]
	v_exp_f32_e32 v226, v226
	v_exp_f32_e32 v227, v227
	v_exp_f32_e32 v228, v228
	v_exp_f32_e32 v229, v229
	v_exp_f32_e32 v230, v230
	v_exp_f32_e32 v231, v231
	v_exp_f32_e32 v232, v232
	v_exp_f32_e32 v233, v233
	v_pk_fma_f32 v[226:227], v[226:227], v[220:221], v[220:221]
	v_pk_fma_f32 v[228:229], v[228:229], v[220:221], v[220:221]
	v_pk_fma_f32 v[230:231], v[230:231], v[220:221], v[220:221]
	v_pk_fma_f32 v[232:233], v[232:233], v[220:221], v[220:221]
	v_rcp_f32_e32 v226, v226
	v_rcp_f32_e32 v227, v227
	v_rcp_f32_e32 v228, v228
	v_rcp_f32_e32 v229, v229
	v_rcp_f32_e32 v230, v230
	v_rcp_f32_e32 v231, v231
	v_rcp_f32_e32 v232, v232
	v_rcp_f32_e32 v233, v233
	v_pk_mul_f32 v[78:79], v[78:79], v[74:75]
	v_pk_mul_f32 v[80:81], v[80:81], v[76:77]
	v_pk_mul_f32 v[70:71], v[70:71], v[66:67]
	v_pk_mul_f32 v[72:73], v[72:73], v[68:69]
	v_pk_mul_f32 v[78:79], v[78:79], v[226:227]
	v_pk_mul_f32 v[80:81], v[80:81], v[228:229]
	v_pk_mul_f32 v[70:71], v[70:71], v[230:231]
	v_pk_mul_f32 v[72:73], v[72:73], v[232:233]
	v_add_u32_e32 v223, 0x28000, v222
	v_cvt_pk_fp8_f32 v234, v78, v79
	v_cvt_pk_fp8_f32 v235, v70, v71
	v_cvt_pk_fp8_f32 v234, v80, v81 op_sel:[0,0,1]
	v_cvt_pk_fp8_f32 v235, v72, v73 op_sel:[0,0,1]
	s_nop 0
	global_store_dwordx2 v223, v[234:235], s[70:71]
	s_mov_b32 s100, 1
	v_pk_mul_f32 v[226:227], v[62:63], v[218:219]
	v_pk_mul_f32 v[228:229], v[64:65], v[218:219]
	v_pk_mul_f32 v[230:231], v[54:55], v[218:219]
	v_pk_mul_f32 v[232:233], v[56:57], v[218:219]
	v_exp_f32_e32 v226, v226
	v_exp_f32_e32 v227, v227
	v_exp_f32_e32 v228, v228
	v_exp_f32_e32 v229, v229
	v_exp_f32_e32 v230, v230
	v_exp_f32_e32 v231, v231
	v_exp_f32_e32 v232, v232
	v_exp_f32_e32 v233, v233
	v_pk_fma_f32 v[226:227], v[226:227], v[220:221], v[220:221]
	v_pk_fma_f32 v[228:229], v[228:229], v[220:221], v[220:221]
	v_pk_fma_f32 v[230:231], v[230:231], v[220:221], v[220:221]
	v_pk_fma_f32 v[232:233], v[232:233], v[220:221], v[220:221]
	v_rcp_f32_e32 v226, v226
	v_rcp_f32_e32 v227, v227
	v_rcp_f32_e32 v228, v228
	v_rcp_f32_e32 v229, v229
	v_rcp_f32_e32 v230, v230
	v_rcp_f32_e32 v231, v231
	v_rcp_f32_e32 v232, v232
	v_rcp_f32_e32 v233, v233
	v_pk_mul_f32 v[62:63], v[62:63], v[58:59]
	v_pk_mul_f32 v[64:65], v[64:65], v[60:61]
	v_pk_mul_f32 v[54:55], v[54:55], v[50:51]
	v_pk_mul_f32 v[56:57], v[56:57], v[52:53]
	v_pk_mul_f32 v[62:63], v[62:63], v[226:227]
	v_pk_mul_f32 v[64:65], v[64:65], v[228:229]
	v_pk_mul_f32 v[54:55], v[54:55], v[230:231]
	v_pk_mul_f32 v[56:57], v[56:57], v[232:233]
	v_add_u32_e32 v225, 0x2c000, v222
	v_cvt_pk_fp8_f32 v236, v62, v63
	v_cvt_pk_fp8_f32 v237, v54, v55
	v_cvt_pk_fp8_f32 v236, v64, v65 op_sel:[0,0,1]
	v_cvt_pk_fp8_f32 v237, v56, v57 op_sel:[0,0,1]
	s_nop 0
	global_store_dwordx2 v225, v[236:237], s[70:71]
	s_mov_b32 s100, 1
	s_and_b64 vcc, exec, s[4:5]
	s_cbranch_vccnz .LBB0_1661

.LBB0_1724:
	ds_read_b128 v[142:145], v137
	ds_read_b128 v[146:149], v137 offset:1024
	ds_read_b128 v[150:153], v137 offset:2048
	ds_read_b128 v[154:157], v137 offset:3072
	s_add_i32 s10, s7, 0xfffd0080
	s_cmp_eq_u32 s85, 4
	s_cselect_b32 s87, s6, s10
	s_cselect_b32 s86, s72, s84
	s_or_b32 s88, s87, 0x80
	s_add_i32 s10, s7, 0xffff0000
	s_mov_b32 m0, s39
	ds_read_b128 v[158:161], v138
	ds_read_b128 v[162:165], v138 offset:1024
	ds_read_b128 v[166:169], v138 offset:2048
	ds_read_b128 v[170:173], v138 offset:3072
	ds_read_b128 v[174:177], v138 offset:4096
	ds_read_b128 v[178:181], v138 offset:5120
	ds_read_b128 v[182:185], v138 offset:6144
	ds_read_b128 v[186:189], v138 offset:7168
	buffer_load_dwordx4 v1, s[44:47], s10 offen lds
	s_mov_b32 m0, s41
	s_nop 0
	buffer_load_dwordx4 v1, s[44:47], s7 offen lds
	s_waitcnt lgkmcnt(8)
	s_barrier
	s_waitcnt lgkmcnt(0)
	s_setprio 1
	s_waitcnt lgkmcnt(4)
	v_mfma_f32_16x16x128_f8f6f4 v[114:117], v[142:149], v[166:173], v[114:117]
	v_mfma_f32_16x16x128_f8f6f4 v[106:109], v[150:157], v[166:173], v[106:109]
	s_waitcnt lgkmcnt(2)
	v_mfma_f32_16x16x128_f8f6f4 v[98:101], v[142:149], v[174:181], v[98:101]
	v_mfma_f32_16x16x128_f8f6f4 v[198:201], v[142:149], v[158:165], v[126:129]
	v_mfma_f32_16x16x128_f8f6f4 v[202:205], v[150:157], v[158:165], v[122:125]
	v_mfma_f32_16x16x128_f8f6f4 v[206:209], v[150:157], v[174:181], v[90:93]
	s_waitcnt lgkmcnt(0)
	v_mfma_f32_16x16x128_f8f6f4 v[210:213], v[142:149], v[182:189], v[82:85]
	v_mfma_f32_16x16x128_f8f6f4 v[214:217], v[150:157], v[182:189], v[74:77]
	s_setprio 0
	s_barrier
	s_mov_b32 m0, s23
	s_mov_b32 s10, s46
	s_mov_b32 s11, s47
	ds_read_b128 v[122:125], v139
	ds_read_b128 v[126:129], v139 offset:1024
	ds_read_b128 v[190:193], v139 offset:2048
	ds_read_b128 v[194:197], v139 offset:3072
	buffer_load_dwordx4 v134, s[8:11], s86 offen lds
	s_add_i32 s33, s86, 0x10000
	s_mov_b32 m0, s24
	s_nop 0
	buffer_load_dwordx4 v134, s[8:11], s33 offen lds
	s_barrier
	s_waitcnt lgkmcnt(0)
	s_setprio 1
	s_waitcnt lgkmcnt(2)
	v_mfma_f32_16x16x128_f8f6f4 v[118:121], v[122:129], v[158:165], v[118:121]
	s_waitcnt lgkmcnt(0)
	v_mfma_f32_16x16x128_f8f6f4 v[110:113], v[190:197], v[158:165], v[110:113]
	v_mfma_f32_16x16x128_f8f6f4 v[102:105], v[122:129], v[166:173], v[102:105]
	v_mfma_f32_16x16x128_f8f6f4 v[158:161], v[190:197], v[166:173], v[94:97]
	v_mfma_f32_16x16x128_f8f6f4 v[162:165], v[122:129], v[174:181], v[86:89]
	v_mfma_f32_16x16x128_f8f6f4 v[166:169], v[190:197], v[174:181], v[78:81]
	v_mfma_f32_16x16x128_f8f6f4 v[170:173], v[122:129], v[182:189], v[70:73]
	v_mfma_f32_16x16x128_f8f6f4 v[174:177], v[190:197], v[182:189], v[18:21]
	s_setprio 0
	s_mov_b32 m0, s22
	s_barrier
	ds_read_b128 v[66:69], v138 offset:16384
	s_nop 1
	ds_read_b128 v[70:73], v138 offset:17408
	ds_read_b128 v[74:77], v138 offset:18432
	ds_read_b128 v[78:81], v138 offset:19456
	ds_read_b128 v[82:85], v138 offset:20480
	ds_read_b128 v[86:89], v138 offset:21504
	ds_read_b128 v[90:93], v138 offset:22528
	ds_read_b128 v[94:97], v138 offset:23552
	buffer_load_dwordx4 v1, s[44:47], s87 offen lds
	s_add_i32 s33, s87, 0x10000
	s_mov_b32 m0, s25
	s_nop 0
	buffer_load_dwordx4 v1, s[44:47], s33 offen lds
	s_barrier
	s_waitcnt lgkmcnt(0)
	s_setprio 1
	s_waitcnt lgkmcnt(6)
	v_mfma_f32_16x16x128_f8f6f4 v[62:65], v[142:149], v[66:73], v[62:65]
	v_mfma_f32_16x16x128_f8f6f4 v[58:61], v[150:157], v[66:73], v[58:61]
	s_waitcnt lgkmcnt(4)
	v_mfma_f32_16x16x128_f8f6f4 v[50:53], v[142:149], v[74:81], v[50:53]
	s_waitcnt lgkmcnt(0)
	v_mfma_f32_16x16x128_f8f6f4 v[230:233], v[142:149], v[90:97], v[230:233]
	v_mfma_f32_16x16x128_f8f6f4 v[218:221], v[150:157], v[74:81], v[42:45]
	v_mfma_f32_16x16x128_f8f6f4 v[222:225], v[142:149], v[82:89], v[34:37]
	v_mfma_f32_16x16x128_f8f6f4 v[226:229], v[150:157], v[82:89], v[26:29]
	v_mfma_f32_16x16x128_f8f6f4 v[234:237], v[150:157], v[90:97], v[10:13]
	s_setprio 0
	s_barrier
	s_mov_b32 m0, s26
	s_add_i32 s33, s86, 0x20000
	buffer_load_dwordx4 v134, s[8:11], s33 offen lds
	s_add_i32 s33, s86, 0x30000
	s_mov_b32 m0, s27
	s_nop 0
	buffer_load_dwordx4 v134, s[8:11], s33 offen lds
	s_cmp_eq_u32 s100, 0
	s_cbranch_scc1 .Lfw_8_a
	s_waitcnt vmcnt(16)
	s_mov_b32 s100, 0
	s_branch .Lfw_8_b

.LBB0_2151:
	ds_read_b128 v[130:133], v195
	ds_read_b128 v[134:137], v195 offset:1024
	ds_read_b128 v[138:141], v195 offset:2048
	ds_read_b128 v[142:145], v195 offset:3072
	s_add_i32 s10, s7, 0xfffa0080
	s_cmp_eq_u32 s13, 12
	s_cselect_b32 s78, s6, s10
	s_cselect_b32 s73, s57, s12
	s_or_b32 s79, s78, 0x80
	s_add_i32 s10, s7, 0xfffe0000
	s_mov_b32 m0, s38
	ds_read_b128 v[146:149], v196
	ds_read_b128 v[150:153], v196 offset:1024
	ds_read_b128 v[154:157], v196 offset:2048
	ds_read_b128 v[158:161], v196 offset:3072
	ds_read_b128 v[162:165], v196 offset:4096
	ds_read_b128 v[166:169], v196 offset:5120
	ds_read_b128 v[170:173], v196 offset:6144
	ds_read_b128 v[174:177], v196 offset:7168
	buffer_load_dwordx4 v1, s[48:51], s10 offen lds
	s_mov_b32 m0, s39
	s_nop 0
	buffer_load_dwordx4 v1, s[48:51], s7 offen lds
	s_waitcnt lgkmcnt(8)
	s_barrier
	s_waitcnt lgkmcnt(0)
	s_setprio 1
	s_waitcnt lgkmcnt(7)
	v_mfma_f32_16x16x32_bf16 v[126:129], v[130:133], v[146:149], v[126:129]
	v_mfma_f32_16x16x32_bf16 v[122:125], v[138:141], v[146:149], v[122:125]
	s_waitcnt lgkmcnt(5)
	v_mfma_f32_16x16x32_bf16 v[110:113], v[130:133], v[154:157], v[110:113]
	v_mfma_f32_16x16x32_bf16 v[106:109], v[138:141], v[154:157], v[106:109]
	s_waitcnt lgkmcnt(3)
	v_mfma_f32_16x16x32_bf16 v[94:97], v[130:133], v[162:165], v[94:97]
	v_mfma_f32_16x16x32_bf16 v[90:93], v[138:141], v[162:165], v[90:93]
	s_waitcnt lgkmcnt(1)
	v_mfma_f32_16x16x32_bf16 v[78:81], v[130:133], v[170:173], v[78:81]
	v_mfma_f32_16x16x32_bf16 v[74:77], v[138:141], v[170:173], v[74:77]
	v_mfma_f32_16x16x32_bf16 v[126:129], v[134:137], v[150:153], v[126:129]
	v_mfma_f32_16x16x32_bf16 v[122:125], v[142:145], v[150:153], v[122:125]
	v_mfma_f32_16x16x32_bf16 v[110:113], v[134:137], v[158:161], v[110:113]
	v_mfma_f32_16x16x32_bf16 v[106:109], v[142:145], v[158:161], v[106:109]
	v_mfma_f32_16x16x32_bf16 v[94:97], v[134:137], v[166:169], v[94:97]
	v_mfma_f32_16x16x32_bf16 v[90:93], v[142:145], v[166:169], v[90:93]
	s_waitcnt lgkmcnt(0)
	v_mfma_f32_16x16x32_bf16 v[78:81], v[134:137], v[174:177], v[78:81]
	v_mfma_f32_16x16x32_bf16 v[74:77], v[142:145], v[174:177], v[74:77]
	s_setprio 0
	s_barrier
	s_mov_b32 m0, s16
	s_mov_b32 s10, s50
	s_mov_b32 s11, s51
	ds_read_b128 v[178:181], v197
	ds_read_b128 v[182:185], v197 offset:1024
	ds_read_b128 v[200:203], v197 offset:2048
	ds_read_b128 v[204:207], v197 offset:3072
	buffer_load_dwordx4 v192, s[8:11], s73 offen lds
	s_add_i32 s33, s73, 0x20000
	s_mov_b32 m0, s17
	s_nop 0
	buffer_load_dwordx4 v192, s[8:11], s33 offen lds
	s_barrier
	s_waitcnt lgkmcnt(0)
	s_setprio 1
	s_waitcnt lgkmcnt(3)
	v_mfma_f32_16x16x32_bf16 v[118:121], v[178:181], v[146:149], v[118:121]
	s_waitcnt lgkmcnt(1)
	v_mfma_f32_16x16x32_bf16 v[114:117], v[200:203], v[146:149], v[114:117]
	v_mfma_f32_16x16x32_bf16 v[102:105], v[178:181], v[154:157], v[102:105]
	v_mfma_f32_16x16x32_bf16 v[98:101], v[200:203], v[154:157], v[98:101]
	v_mfma_f32_16x16x32_bf16 v[86:89], v[178:181], v[162:165], v[86:89]
	v_mfma_f32_16x16x32_bf16 v[82:85], v[200:203], v[162:165], v[82:85]
	v_mfma_f32_16x16x32_bf16 v[70:73], v[178:181], v[170:173], v[70:73]
	v_mfma_f32_16x16x32_bf16 v[66:69], v[200:203], v[170:173], v[66:69]
	v_mfma_f32_16x16x32_bf16 v[118:121], v[182:185], v[150:153], v[118:121]
	s_waitcnt lgkmcnt(0)
	v_mfma_f32_16x16x32_bf16 v[114:117], v[204:207], v[150:153], v[114:117]
	v_mfma_f32_16x16x32_bf16 v[102:105], v[182:185], v[158:161], v[102:105]
	v_mfma_f32_16x16x32_bf16 v[98:101], v[204:207], v[158:161], v[98:101]
	v_mfma_f32_16x16x32_bf16 v[86:89], v[182:185], v[166:169], v[86:89]
	v_mfma_f32_16x16x32_bf16 v[82:85], v[204:207], v[166:169], v[82:85]
	v_mfma_f32_16x16x32_bf16 v[70:73], v[182:185], v[174:177], v[70:73]
	v_mfma_f32_16x16x32_bf16 v[66:69], v[204:207], v[174:177], v[66:69]
	s_setprio 0
	s_mov_b32 m0, s15
	s_barrier
	ds_read_b128 v[146:149], v196 offset:16384
	ds_read_b128 v[150:153], v196 offset:17408
	ds_read_b128 v[154:157], v196 offset:18432
	ds_read_b128 v[158:161], v196 offset:19456
	ds_read_b128 v[162:165], v196 offset:20480
	ds_read_b128 v[166:169], v196 offset:21504
	ds_read_b128 v[170:173], v196 offset:22528
	ds_read_b128 v[174:177], v196 offset:23552
	buffer_load_dwordx4 v1, s[48:51], s78 offen lds
	s_add_i32 s33, s78, 0x20000
	s_mov_b32 m0, s18
	s_nop 0
	buffer_load_dwordx4 v1, s[48:51], s33 offen lds
	s_barrier
	s_waitcnt lgkmcnt(0)
	s_setprio 1
	s_waitcnt lgkmcnt(7)
	v_mfma_f32_16x16x32_bf16 v[62:65], v[130:133], v[146:149], v[62:65]
	v_mfma_f32_16x16x32_bf16 v[58:61], v[138:141], v[146:149], v[58:61]
	s_waitcnt lgkmcnt(5)
	v_mfma_f32_16x16x32_bf16 v[46:49], v[130:133], v[154:157], v[46:49]
	v_mfma_f32_16x16x32_bf16 v[42:45], v[138:141], v[154:157], v[42:45]
	s_waitcnt lgkmcnt(3)
	v_mfma_f32_16x16x32_bf16 v[30:33], v[130:133], v[162:165], v[30:33]
	v_mfma_f32_16x16x32_bf16 v[26:29], v[138:141], v[162:165], v[26:29]
	s_waitcnt lgkmcnt(1)
	v_mfma_f32_16x16x32_bf16 v[14:17], v[130:133], v[170:173], v[14:17]
	v_mfma_f32_16x16x32_bf16 v[10:13], v[138:141], v[170:173], v[10:13]
	v_mfma_f32_16x16x32_bf16 v[62:65], v[134:137], v[150:153], v[62:65]
	v_mfma_f32_16x16x32_bf16 v[58:61], v[142:145], v[150:153], v[58:61]
	v_mfma_f32_16x16x32_bf16 v[46:49], v[134:137], v[158:161], v[46:49]
	v_mfma_f32_16x16x32_bf16 v[42:45], v[142:145], v[158:161], v[42:45]
	v_mfma_f32_16x16x32_bf16 v[30:33], v[134:137], v[166:169], v[30:33]
	v_mfma_f32_16x16x32_bf16 v[26:29], v[142:145], v[166:169], v[26:29]
	s_waitcnt lgkmcnt(0)
	v_mfma_f32_16x16x32_bf16 v[14:17], v[134:137], v[174:177], v[14:17]
	v_mfma_f32_16x16x32_bf16 v[10:13], v[142:145], v[174:177], v[10:13]
	s_setprio 0
	s_barrier
	s_mov_b32 m0, s19
	s_add_i32 s33, s73, 0x40000
	buffer_load_dwordx4 v192, s[8:11], s33 offen lds
	s_add_i32 s33, s73, 0x60000
	s_mov_b32 m0, s20
	s_nop 0
	buffer_load_dwordx4 v192, s[8:11], s33 offen lds
	s_cmp_eq_u32 s100, 0
	s_cbranch_scc1 .Lfw_10_a
	s_waitcnt vmcnt(16)
	s_mov_b32 s100, 0
	s_branch .Lfw_10_b

.LBB0_2423:
	v_mov_b32_e32 v218, 0xbd38aa3b
	v_mov_b32_e32 v219, 0xbd38aa3b
	v_mov_b32_e32 v220, 0x44800000
	v_mov_b32_e32 v221, 0x44800000
	v_lshl_add_u32 v222, s47, 8, v187
	v_lshl_or_b32 v224, s46, 7, v188
	s_nop 0
	v_lshl_add_u32 v222, v222, 10, v224
	s_mov_b32 s46, s38
	s_mov_b32 s47, s39
	s_mov_b32 s49, s45
	v_pk_mul_f32 v[226:227], v[174:175], v[218:219]
	v_pk_mul_f32 v[228:229], v[176:177], v[218:219]
	v_pk_mul_f32 v[230:231], v[166:167], v[218:219]
	v_pk_mul_f32 v[232:233], v[168:169], v[218:219]
	v_exp_f32_e32 v226, v226
	v_exp_f32_e32 v227, v227
	v_exp_f32_e32 v228, v228
	v_exp_f32_e32 v229, v229
	v_exp_f32_e32 v230, v230
	v_exp_f32_e32 v231, v231
	v_exp_f32_e32 v232, v232
	v_exp_f32_e32 v233, v233
	v_pk_fma_f32 v[226:227], v[226:227], v[220:221], v[220:221]
	v_pk_fma_f32 v[228:229], v[228:229], v[220:221], v[220:221]
	v_pk_fma_f32 v[230:231], v[230:231], v[220:221], v[220:221]
	v_pk_fma_f32 v[232:233], v[232:233], v[220:221], v[220:221]
	v_rcp_f32_e32 v226, v226
	v_rcp_f32_e32 v227, v227
	v_rcp_f32_e32 v228, v228
	v_rcp_f32_e32 v229, v229
	v_rcp_f32_e32 v230, v230
	v_rcp_f32_e32 v231, v231
	v_rcp_f32_e32 v232, v232
	v_rcp_f32_e32 v233, v233
	v_pk_mul_f32 v[174:175], v[174:175], v[170:171]
	v_pk_mul_f32 v[176:177], v[176:177], v[172:173]
	v_pk_mul_f32 v[166:167], v[166:167], v[162:163]
	v_pk_mul_f32 v[168:169], v[168:169], v[164:165]
	v_pk_mul_f32 v[174:175], v[174:175], v[226:227]
	v_pk_mul_f32 v[176:177], v[176:177], v[228:229]
	v_pk_mul_f32 v[166:167], v[166:167], v[230:231]
	v_pk_mul_f32 v[168:169], v[168:169], v[232:233]
	v_mov_b32_e32 v223, v222
	v_cvt_pk_fp8_f32 v234, v174, v175
	v_cvt_pk_fp8_f32 v235, v166, v167
	v_cvt_pk_fp8_f32 v234, v176, v177 op_sel:[0,0,1]
	v_cvt_pk_fp8_f32 v235, v168, v169 op_sel:[0,0,1]
	s_nop 0
	global_store_dwordx2 v223, v[234:235], s[70:71]
	s_mov_b32 s100, 1
	v_pk_mul_f32 v[226:227], v[158:159], v[218:219]
	v_pk_mul_f32 v[228:229], v[160:161], v[218:219]
	v_pk_mul_f32 v[230:231], v[150:151], v[218:219]
	v_pk_mul_f32 v[232:233], v[152:153], v[218:219]
	v_exp_f32_e32 v226, v226
	v_exp_f32_e32 v227, v227
	v_exp_f32_e32 v228, v228
	v_exp_f32_e32 v229, v229
	v_exp_f32_e32 v230, v230
	v_exp_f32_e32 v231, v231
	v_exp_f32_e32 v232, v232
	v_exp_f32_e32 v233, v233
	v_pk_fma_f32 v[226:227], v[226:227], v[220:221], v[220:221]
	v_pk_fma_f32 v[228:229], v[228:229], v[220:221], v[220:221]
	v_pk_fma_f32 v[230:231], v[230:231], v[220:221], v[220:221]
	v_pk_fma_f32 v[232:233], v[232:233], v[220:221], v[220:221]
	v_rcp_f32_e32 v226, v226
	v_rcp_f32_e32 v227, v227
	v_rcp_f32_e32 v228, v228
	v_rcp_f32_e32 v229, v229
	v_rcp_f32_e32 v230, v230
	v_rcp_f32_e32 v231, v231
	v_rcp_f32_e32 v232, v232
	v_rcp_f32_e32 v233, v233
	v_pk_mul_f32 v[158:159], v[158:159], v[154:155]
	v_pk_mul_f32 v[160:161], v[160:161], v[156:157]
	v_pk_mul_f32 v[150:151], v[150:151], v[146:147]
	v_pk_mul_f32 v[152:153], v[152:153], v[148:149]
	v_pk_mul_f32 v[158:159], v[158:159], v[226:227]
	v_pk_mul_f32 v[160:161], v[160:161], v[228:229]
	v_pk_mul_f32 v[150:151], v[150:151], v[230:231]
	v_pk_mul_f32 v[152:153], v[152:153], v[232:233]
	v_add_u32_e32 v225, 0x4000, v222
	v_cvt_pk_fp8_f32 v236, v158, v159
	v_cvt_pk_fp8_f32 v237, v150, v151
	v_cvt_pk_fp8_f32 v236, v160, v161 op_sel:[0,0,1]
	v_cvt_pk_fp8_f32 v237, v152, v153 op_sel:[0,0,1]
	s_nop 0
	global_store_dwordx2 v225, v[236:237], s[70:71]
	s_mov_b32 s100, 1
	v_pk_mul_f32 v[226:227], v[142:143], v[218:219]
	v_pk_mul_f32 v[228:229], v[144:145], v[218:219]
	v_pk_mul_f32 v[230:231], v[134:135], v[218:219]
	v_pk_mul_f32 v[232:233], v[136:137], v[218:219]
	v_exp_f32_e32 v226, v226
	v_exp_f32_e32 v227, v227
	v_exp_f32_e32 v228, v228
	v_exp_f32_e32 v229, v229
	v_exp_f32_e32 v230, v230
	v_exp_f32_e32 v231, v231
	v_exp_f32_e32 v232, v232
	v_exp_f32_e32 v233, v233
	v_pk_fma_f32 v[226:227], v[226:227], v[220:221], v[220:221]
	v_pk_fma_f32 v[228:229], v[228:229], v[220:221], v[220:221]
	v_pk_fma_f32 v[230:231], v[230:231], v[220:221], v[220:221]
	v_pk_fma_f32 v[232:233], v[232:233], v[220:221], v[220:221]
	v_rcp_f32_e32 v226, v226
	v_rcp_f32_e32 v227, v227
	v_rcp_f32_e32 v228, v228
	v_rcp_f32_e32 v229, v229
	v_rcp_f32_e32 v230, v230
	v_rcp_f32_e32 v231, v231
	v_rcp_f32_e32 v232, v232
	v_rcp_f32_e32 v233, v233
	v_pk_mul_f32 v[142:143], v[142:143], v[138:139]
	v_pk_mul_f32 v[144:145], v[144:145], v[140:141]
	v_pk_mul_f32 v[134:135], v[134:135], v[130:131]
	v_pk_mul_f32 v[136:137], v[136:137], v[132:133]
	v_pk_mul_f32 v[142:143], v[142:143], v[226:227]
	v_pk_mul_f32 v[144:145], v[144:145], v[228:229]
	v_pk_mul_f32 v[134:135], v[134:135], v[230:231]
	v_pk_mul_f32 v[136:137], v[136:137], v[232:233]
	v_add_u32_e32 v223, 0x8000, v222
	v_cvt_pk_fp8_f32 v234, v142, v143
	v_cvt_pk_fp8_f32 v235, v134, v135
	v_cvt_pk_fp8_f32 v234, v144, v145 op_sel:[0,0,1]
	v_cvt_pk_fp8_f32 v235, v136, v137 op_sel:[0,0,1]
	s_nop 0
	global_store_dwordx2 v223, v[234:235], s[70:71]
	s_mov_b32 s100, 1
	v_pk_mul_f32 v[226:227], v[126:127], v[218:219]
	v_pk_mul_f32 v[228:229], v[128:129], v[218:219]
	v_pk_mul_f32 v[230:231], v[118:119], v[218:219]
	v_pk_mul_f32 v[232:233], v[120:121], v[218:219]
	v_exp_f32_e32 v226, v226
	v_exp_f32_e32 v227, v227
	v_exp_f32_e32 v228, v228
	v_exp_f32_e32 v229, v229
	v_exp_f32_e32 v230, v230
	v_exp_f32_e32 v231, v231
	v_exp_f32_e32 v232, v232
	v_exp_f32_e32 v233, v233
	v_pk_fma_f32 v[226:227], v[226:227], v[220:221], v[220:221]
	v_pk_fma_f32 v[228:229], v[228:229], v[220:221], v[220:221]
	v_pk_fma_f32 v[230:231], v[230:231], v[220:221], v[220:221]
	v_pk_fma_f32 v[232:233], v[232:233], v[220:221], v[220:221]
	v_rcp_f32_e32 v226, v226
	v_rcp_f32_e32 v227, v227
	v_rcp_f32_e32 v228, v228
	v_rcp_f32_e32 v229, v229
	v_rcp_f32_e32 v230, v230
	v_rcp_f32_e32 v231, v231
	v_rcp_f32_e32 v232, v232
	v_rcp_f32_e32 v233, v233
	v_pk_mul_f32 v[126:127], v[126:127], v[122:123]
	v_pk_mul_f32 v[128:129], v[128:129], v[124:125]
	v_pk_mul_f32 v[118:119], v[118:119], v[114:115]
	v_pk_mul_f32 v[120:121], v[120:121], v[116:117]
	v_pk_mul_f32 v[126:127], v[126:127], v[226:227]
	v_pk_mul_f32 v[128:129], v[128:129], v[228:229]
	v_pk_mul_f32 v[118:119], v[118:119], v[230:231]
	v_pk_mul_f32 v[120:121], v[120:121], v[232:233]
	v_add_u32_e32 v225, 0xc000, v222
	v_cvt_pk_fp8_f32 v236, v126, v127
	v_cvt_pk_fp8_f32 v237, v118, v119
	v_cvt_pk_fp8_f32 v236, v128, v129 op_sel:[0,0,1]
	v_cvt_pk_fp8_f32 v237, v120, v121 op_sel:[0,0,1]
	s_nop 0
	global_store_dwordx2 v225, v[236:237], s[70:71]
	s_mov_b32 s100, 1
	v_pk_mul_f32 v[226:227], v[110:111], v[218:219]
	v_pk_mul_f32 v[228:229], v[112:113], v[218:219]
	v_pk_mul_f32 v[230:231], v[102:103], v[218:219]
	v_pk_mul_f32 v[232:233], v[104:105], v[218:219]
	v_exp_f32_e32 v226, v226
	v_exp_f32_e32 v227, v227
	v_exp_f32_e32 v228, v228
	v_exp_f32_e32 v229, v229
	v_exp_f32_e32 v230, v230
	v_exp_f32_e32 v231, v231
	v_exp_f32_e32 v232, v232
	v_exp_f32_e32 v233, v233
	v_pk_fma_f32 v[226:227], v[226:227], v[220:221], v[220:221]
	v_pk_fma_f32 v[228:229], v[228:229], v[220:221], v[220:221]
	v_pk_fma_f32 v[230:231], v[230:231], v[220:221], v[220:221]
	v_pk_fma_f32 v[232:233], v[232:233], v[220:221], v[220:221]
	v_rcp_f32_e32 v226, v226
	v_rcp_f32_e32 v227, v227
	v_rcp_f32_e32 v228, v228
	v_rcp_f32_e32 v229, v229
	v_rcp_f32_e32 v230, v230
	v_rcp_f32_e32 v231, v231
	v_rcp_f32_e32 v232, v232
	v_rcp_f32_e32 v233, v233
	v_pk_mul_f32 v[110:111], v[110:111], v[106:107]
	v_pk_mul_f32 v[112:113], v[112:113], v[108:109]
	v_pk_mul_f32 v[102:103], v[102:103], v[98:99]
	v_pk_mul_f32 v[104:105], v[104:105], v[100:101]
	v_pk_mul_f32 v[110:111], v[110:111], v[226:227]
	v_pk_mul_f32 v[112:113], v[112:113], v[228:229]
	v_pk_mul_f32 v[102:103], v[102:103], v[230:231]
	v_pk_mul_f32 v[104:105], v[104:105], v[232:233]
	v_add_u32_e32 v223, 0x20000, v222
	v_cvt_pk_fp8_f32 v234, v110, v111
	v_cvt_pk_fp8_f32 v235, v102, v103
	v_cvt_pk_fp8_f32 v234, v112, v113 op_sel:[0,0,1]
	v_cvt_pk_fp8_f32 v235, v104, v105 op_sel:[0,0,1]
	s_nop 0
	global_store_dwordx2 v223, v[234:235], s[70:71]
	s_mov_b32 s100, 1
	v_pk_mul_f32 v[226:227], v[94:95], v[218:219]
	v_pk_mul_f32 v[228:229], v[96:97], v[218:219]
	v_pk_mul_f32 v[230:231], v[86:87], v[218:219]
	v_pk_mul_f32 v[232:233], v[88:89], v[218:219]
	v_exp_f32_e32 v226, v226
	v_exp_f32_e32 v227, v227
	v_exp_f32_e32 v228, v228
	v_exp_f32_e32 v229, v229
	v_exp_f32_e32 v230, v230
	v_exp_f32_e32 v231, v231
	v_exp_f32_e32 v232, v232
	v_exp_f32_e32 v233, v233
	v_pk_fma_f32 v[226:227], v[226:227], v[220:221], v[220:221]
	v_pk_fma_f32 v[228:229], v[228:229], v[220:221], v[220:221]
	v_pk_fma_f32 v[230:231], v[230:231], v[220:221], v[220:221]
	v_pk_fma_f32 v[232:233], v[232:233], v[220:221], v[220:221]
	v_rcp_f32_e32 v226, v226
	v_rcp_f32_e32 v227, v227
	v_rcp_f32_e32 v228, v228
	v_rcp_f32_e32 v229, v229
	v_rcp_f32_e32 v230, v230
	v_rcp_f32_e32 v231, v231
	v_rcp_f32_e32 v232, v232
	v_rcp_f32_e32 v233, v233
	v_pk_mul_f32 v[94:95], v[94:95], v[90:91]
	v_pk_mul_f32 v[96:97], v[96:97], v[92:93]
	v_pk_mul_f32 v[86:87], v[86:87], v[82:83]
	v_pk_mul_f32 v[88:89], v[88:89], v[84:85]
	v_pk_mul_f32 v[94:95], v[94:95], v[226:227]
	v_pk_mul_f32 v[96:97], v[96:97], v[228:229]
	v_pk_mul_f32 v[86:87], v[86:87], v[230:231]
	v_pk_mul_f32 v[88:89], v[88:89], v[232:233]
	v_add_u32_e32 v225, 0x24000, v222
	v_cvt_pk_fp8_f32 v236, v94, v95
	v_cvt_pk_fp8_f32 v237, v86, v87
	v_cvt_pk_fp8_f32 v236, v96, v97 op_sel:[0,0,1]
	v_cvt_pk_fp8_f32 v237, v88, v89 op_sel:[0,0,1]
	s_nop 0
	global_store_dwordx2 v225, v[236:237], s[70:71]
	s_mov_b32 s100, 1
	v_pk_mul_f32 v[226:227], v[78:79], v[218:219]
	v_pk_mul_f32 v[228:229], v[80:81], v[218:219]
	v_pk_mul_f32 v[230:231], v[70:71], v[218:219]
	v_pk_mul_f32 v[232:233], v[72:73], v[218:219]
	v_exp_f32_e32 v226, v226
	v_exp_f32_e32 v227, v227
	v_exp_f32_e32 v228, v228
	v_exp_f32_e32 v229, v229
	v_exp_f32_e32 v230, v230
	v_exp_f32_e32 v231, v231
	v_exp_f32_e32 v232, v232
	v_exp_f32_e32 v233, v233
	v_pk_fma_f32 v[226:227], v[226:227], v[220:221], v[220:221]
	v_pk_fma_f32 v[228:229], v[228:229], v[220:221], v[220:221]
	v_pk_fma_f32 v[230:231], v[230:231], v[220:221], v[220:221]
	v_pk_fma_f32 v[232:233], v[232:233], v[220:221], v[220:221]
	v_rcp_f32_e32 v226, v226
	v_rcp_f32_e32 v227, v227
	v_rcp_f32_e32 v228, v228
	v_rcp_f32_e32 v229, v229
	v_rcp_f32_e32 v230, v230
	v_rcp_f32_e32 v231, v231
	v_rcp_f32_e32 v232, v232
	v_rcp_f32_e32 v233, v233
	v_pk_mul_f32 v[78:79], v[78:79], v[74:75]
	v_pk_mul_f32 v[80:81], v[80:81], v[76:77]
	v_pk_mul_f32 v[70:71], v[70:71], v[66:67]
	v_pk_mul_f32 v[72:73], v[72:73], v[68:69]
	v_pk_mul_f32 v[78:79], v[78:79], v[226:227]
	v_pk_mul_f32 v[80:81], v[80:81], v[228:229]
	v_pk_mul_f32 v[70:71], v[70:71], v[230:231]
	v_pk_mul_f32 v[72:73], v[72:73], v[232:233]
	v_add_u32_e32 v223, 0x28000, v222
	v_cvt_pk_fp8_f32 v234, v78, v79
	v_cvt_pk_fp8_f32 v235, v70, v71
	v_cvt_pk_fp8_f32 v234, v80, v81 op_sel:[0,0,1]
	v_cvt_pk_fp8_f32 v235, v72, v73 op_sel:[0,0,1]
	s_nop 0
	global_store_dwordx2 v223, v[234:235], s[70:71]
	s_mov_b32 s100, 1
	v_pk_mul_f32 v[226:227], v[62:63], v[218:219]
	v_pk_mul_f32 v[228:229], v[64:65], v[218:219]
	v_pk_mul_f32 v[230:231], v[54:55], v[218:219]
	v_pk_mul_f32 v[232:233], v[56:57], v[218:219]
	v_exp_f32_e32 v226, v226
	v_exp_f32_e32 v227, v227
	v_exp_f32_e32 v228, v228
	v_exp_f32_e32 v229, v229
	v_exp_f32_e32 v230, v230
	v_exp_f32_e32 v231, v231
	v_exp_f32_e32 v232, v232
	v_exp_f32_e32 v233, v233
	v_pk_fma_f32 v[226:227], v[226:227], v[220:221], v[220:221]
	v_pk_fma_f32 v[228:229], v[228:229], v[220:221], v[220:221]
	v_pk_fma_f32 v[230:231], v[230:231], v[220:221], v[220:221]
	v_pk_fma_f32 v[232:233], v[232:233], v[220:221], v[220:221]
	v_rcp_f32_e32 v226, v226
	v_rcp_f32_e32 v227, v227
	v_rcp_f32_e32 v228, v228
	v_rcp_f32_e32 v229, v229
	v_rcp_f32_e32 v230, v230
	v_rcp_f32_e32 v231, v231
	v_rcp_f32_e32 v232, v232
	v_rcp_f32_e32 v233, v233
	v_pk_mul_f32 v[62:63], v[62:63], v[58:59]
	v_pk_mul_f32 v[64:65], v[64:65], v[60:61]
	v_pk_mul_f32 v[54:55], v[54:55], v[50:51]
	v_pk_mul_f32 v[56:57], v[56:57], v[52:53]
	v_pk_mul_f32 v[62:63], v[62:63], v[226:227]
	v_pk_mul_f32 v[64:65], v[64:65], v[228:229]
	v_pk_mul_f32 v[54:55], v[54:55], v[230:231]
	v_pk_mul_f32 v[56:57], v[56:57], v[232:233]
	v_add_u32_e32 v225, 0x2c000, v222
	v_cvt_pk_fp8_f32 v236, v62, v63
	v_cvt_pk_fp8_f32 v237, v54, v55
	v_cvt_pk_fp8_f32 v236, v64, v65 op_sel:[0,0,1]
	v_cvt_pk_fp8_f32 v237, v56, v57 op_sel:[0,0,1]
	s_nop 0
	global_store_dwordx2 v225, v[236:237], s[70:71]
	s_mov_b32 s100, 1
	s_and_b64 vcc, exec, s[4:5]
	s_cbranch_vccnz .LBB0_2438

.LBB0_2509:
	ds_read_b128 v[142:145], v137
	ds_read_b128 v[146:149], v137 offset:1024
	ds_read_b128 v[150:153], v137 offset:2048
	ds_read_b128 v[154:157], v137 offset:3072
	s_add_i32 s10, s7, 0xfffd0080
	s_cmp_eq_u32 s84, 4
	s_cselect_b32 s86, s6, s10
	s_cselect_b32 s85, s59, s79
	s_or_b32 s87, s86, 0x80
	s_add_i32 s10, s7, 0xffff0000
	s_mov_b32 m0, s38
	ds_read_b128 v[158:161], v138
	ds_read_b128 v[162:165], v138 offset:1024
	ds_read_b128 v[166:169], v138 offset:2048
	ds_read_b128 v[170:173], v138 offset:3072
	ds_read_b128 v[174:177], v138 offset:4096
	ds_read_b128 v[178:181], v138 offset:5120
	ds_read_b128 v[182:185], v138 offset:6144
	ds_read_b128 v[186:189], v138 offset:7168
	buffer_load_dwordx4 v1, s[44:47], s10 offen lds
	s_mov_b32 m0, s39
	s_nop 0
	buffer_load_dwordx4 v1, s[44:47], s7 offen lds
	s_waitcnt lgkmcnt(8)
	s_barrier
	s_waitcnt lgkmcnt(0)
	s_setprio 1
	s_waitcnt lgkmcnt(4)
	v_mfma_f32_16x16x128_f8f6f4 v[114:117], v[142:149], v[166:173], v[114:117]
	v_mfma_f32_16x16x128_f8f6f4 v[106:109], v[150:157], v[166:173], v[106:109]
	s_waitcnt lgkmcnt(2)
	v_mfma_f32_16x16x128_f8f6f4 v[98:101], v[142:149], v[174:181], v[98:101]
	v_mfma_f32_16x16x128_f8f6f4 v[198:201], v[142:149], v[158:165], v[126:129]
	v_mfma_f32_16x16x128_f8f6f4 v[202:205], v[150:157], v[158:165], v[122:125]
	v_mfma_f32_16x16x128_f8f6f4 v[206:209], v[150:157], v[174:181], v[90:93]
	s_waitcnt lgkmcnt(0)
	v_mfma_f32_16x16x128_f8f6f4 v[210:213], v[142:149], v[182:189], v[82:85]
	v_mfma_f32_16x16x128_f8f6f4 v[214:217], v[150:157], v[182:189], v[74:77]
	s_setprio 0
	s_barrier
	s_mov_b32 m0, s22
	s_mov_b32 s10, s46
	s_mov_b32 s11, s47
	ds_read_b128 v[122:125], v139
	ds_read_b128 v[126:129], v139 offset:1024
	ds_read_b128 v[190:193], v139 offset:2048
	ds_read_b128 v[194:197], v139 offset:3072
	buffer_load_dwordx4 v134, s[8:11], s85 offen lds
	s_add_i32 s33, s85, 0x10000
	s_mov_b32 m0, s23
	s_nop 0
	buffer_load_dwordx4 v134, s[8:11], s33 offen lds
	s_barrier
	s_waitcnt lgkmcnt(0)
	s_setprio 1
	s_waitcnt lgkmcnt(2)
	v_mfma_f32_16x16x128_f8f6f4 v[118:121], v[122:129], v[158:165], v[118:121]
	s_waitcnt lgkmcnt(0)
	v_mfma_f32_16x16x128_f8f6f4 v[110:113], v[190:197], v[158:165], v[110:113]
	v_mfma_f32_16x16x128_f8f6f4 v[102:105], v[122:129], v[166:173], v[102:105]
	v_mfma_f32_16x16x128_f8f6f4 v[158:161], v[190:197], v[166:173], v[94:97]
	v_mfma_f32_16x16x128_f8f6f4 v[162:165], v[122:129], v[174:181], v[86:89]
	v_mfma_f32_16x16x128_f8f6f4 v[166:169], v[190:197], v[174:181], v[78:81]
	v_mfma_f32_16x16x128_f8f6f4 v[170:173], v[122:129], v[182:189], v[70:73]
	v_mfma_f32_16x16x128_f8f6f4 v[174:177], v[190:197], v[182:189], v[18:21]
	s_setprio 0
	s_mov_b32 m0, s21
	s_barrier
	ds_read_b128 v[66:69], v138 offset:16384
	s_nop 1
	ds_read_b128 v[70:73], v138 offset:17408
	ds_read_b128 v[74:77], v138 offset:18432
	ds_read_b128 v[78:81], v138 offset:19456
	ds_read_b128 v[82:85], v138 offset:20480
	ds_read_b128 v[86:89], v138 offset:21504
	ds_read_b128 v[90:93], v138 offset:22528
	ds_read_b128 v[94:97], v138 offset:23552
	buffer_load_dwordx4 v1, s[44:47], s86 offen lds
	s_add_i32 s33, s86, 0x10000
	s_mov_b32 m0, s24
	s_nop 0
	buffer_load_dwordx4 v1, s[44:47], s33 offen lds
	s_barrier
	s_waitcnt lgkmcnt(0)
	s_setprio 1
	s_waitcnt lgkmcnt(6)
	v_mfma_f32_16x16x128_f8f6f4 v[62:65], v[142:149], v[66:73], v[62:65]
	v_mfma_f32_16x16x128_f8f6f4 v[58:61], v[150:157], v[66:73], v[58:61]
	s_waitcnt lgkmcnt(4)
	v_mfma_f32_16x16x128_f8f6f4 v[50:53], v[142:149], v[74:81], v[50:53]
	s_waitcnt lgkmcnt(0)
	v_mfma_f32_16x16x128_f8f6f4 v[230:233], v[142:149], v[90:97], v[230:233]
	v_mfma_f32_16x16x128_f8f6f4 v[218:221], v[150:157], v[74:81], v[42:45]
	v_mfma_f32_16x16x128_f8f6f4 v[222:225], v[142:149], v[82:89], v[34:37]
	v_mfma_f32_16x16x128_f8f6f4 v[226:229], v[150:157], v[82:89], v[26:29]
	v_mfma_f32_16x16x128_f8f6f4 v[234:237], v[150:157], v[90:97], v[10:13]
	s_setprio 0
	s_barrier
	s_mov_b32 m0, s25
	s_add_i32 s33, s85, 0x20000
	buffer_load_dwordx4 v134, s[8:11], s33 offen lds
	s_add_i32 s33, s85, 0x30000
	s_mov_b32 m0, s26
	s_nop 0
	buffer_load_dwordx4 v134, s[8:11], s33 offen lds
	s_cmp_eq_u32 s100, 0
	s_cbranch_scc1 .Lfw_12_a
	s_waitcnt vmcnt(16)
	s_mov_b32 s100, 0
	s_branch .Lfw_12_b

.LBB0_2827:
	ds_read_b128 v[130:133], v196
	ds_read_b128 v[134:137], v196 offset:1024
	ds_read_b128 v[138:141], v196 offset:2048
	ds_read_b128 v[142:145], v196 offset:3072
	s_add_i32 s10, s7, 0xfffa0080
	s_cmp_eq_u32 s13, 12
	s_cselect_b32 s78, s6, s10
	s_cselect_b32 s73, s57, s12
	s_or_b32 s79, s78, 0x80
	s_add_i32 s10, s7, 0xfffe0000
	s_mov_b32 m0, s38
	ds_read_b128 v[146:149], v197
	ds_read_b128 v[150:153], v197 offset:1024
	ds_read_b128 v[154:157], v197 offset:2048
	ds_read_b128 v[158:161], v197 offset:3072
	ds_read_b128 v[162:165], v197 offset:4096
	ds_read_b128 v[166:169], v197 offset:5120
	ds_read_b128 v[170:173], v197 offset:6144
	ds_read_b128 v[174:177], v197 offset:7168
	buffer_load_dwordx4 v192, s[48:51], s10 offen lds
	s_mov_b32 m0, s39
	s_nop 0
	buffer_load_dwordx4 v192, s[48:51], s7 offen lds
	s_waitcnt lgkmcnt(8)
	s_barrier
	s_waitcnt lgkmcnt(0)
	s_setprio 1
	s_waitcnt lgkmcnt(7)
	v_mfma_f32_16x16x32_bf16 v[126:129], v[130:133], v[146:149], v[126:129]
	v_mfma_f32_16x16x32_bf16 v[122:125], v[138:141], v[146:149], v[122:125]
	s_waitcnt lgkmcnt(5)
	v_mfma_f32_16x16x32_bf16 v[110:113], v[130:133], v[154:157], v[110:113]
	v_mfma_f32_16x16x32_bf16 v[106:109], v[138:141], v[154:157], v[106:109]
	s_waitcnt lgkmcnt(3)
	v_mfma_f32_16x16x32_bf16 v[94:97], v[130:133], v[162:165], v[94:97]
	v_mfma_f32_16x16x32_bf16 v[90:93], v[138:141], v[162:165], v[90:93]
	s_waitcnt lgkmcnt(1)
	v_mfma_f32_16x16x32_bf16 v[78:81], v[130:133], v[170:173], v[78:81]
	v_mfma_f32_16x16x32_bf16 v[74:77], v[138:141], v[170:173], v[74:77]
	v_mfma_f32_16x16x32_bf16 v[126:129], v[134:137], v[150:153], v[126:129]
	v_mfma_f32_16x16x32_bf16 v[122:125], v[142:145], v[150:153], v[122:125]
	v_mfma_f32_16x16x32_bf16 v[110:113], v[134:137], v[158:161], v[110:113]
	v_mfma_f32_16x16x32_bf16 v[106:109], v[142:145], v[158:161], v[106:109]
	v_mfma_f32_16x16x32_bf16 v[94:97], v[134:137], v[166:169], v[94:97]
	v_mfma_f32_16x16x32_bf16 v[90:93], v[142:145], v[166:169], v[90:93]
	s_waitcnt lgkmcnt(0)
	v_mfma_f32_16x16x32_bf16 v[78:81], v[134:137], v[174:177], v[78:81]
	v_mfma_f32_16x16x32_bf16 v[74:77], v[142:145], v[174:177], v[74:77]
	s_setprio 0
	s_barrier
	s_mov_b32 m0, s16
	s_mov_b32 s10, s50
	s_mov_b32 s11, s51
	ds_read_b128 v[178:181], v198
	ds_read_b128 v[182:185], v198 offset:1024
	ds_read_b128 v[202:205], v198 offset:2048
	ds_read_b128 v[206:209], v198 offset:3072
	buffer_load_dwordx4 v193, s[8:11], s73 offen lds
	s_add_i32 s33, s73, 0x20000
	s_mov_b32 m0, s17
	s_nop 0
	buffer_load_dwordx4 v193, s[8:11], s33 offen lds
	s_barrier
	s_waitcnt lgkmcnt(0)
	s_setprio 1
	s_waitcnt lgkmcnt(3)
	v_mfma_f32_16x16x32_bf16 v[118:121], v[178:181], v[146:149], v[118:121]
	s_waitcnt lgkmcnt(1)
	v_mfma_f32_16x16x32_bf16 v[114:117], v[202:205], v[146:149], v[114:117]
	v_mfma_f32_16x16x32_bf16 v[102:105], v[178:181], v[154:157], v[102:105]
	v_mfma_f32_16x16x32_bf16 v[98:101], v[202:205], v[154:157], v[98:101]
	v_mfma_f32_16x16x32_bf16 v[86:89], v[178:181], v[162:165], v[86:89]
	v_mfma_f32_16x16x32_bf16 v[82:85], v[202:205], v[162:165], v[82:85]
	v_mfma_f32_16x16x32_bf16 v[70:73], v[178:181], v[170:173], v[70:73]
	v_mfma_f32_16x16x32_bf16 v[66:69], v[202:205], v[170:173], v[66:69]
	v_mfma_f32_16x16x32_bf16 v[118:121], v[182:185], v[150:153], v[118:121]
	s_waitcnt lgkmcnt(0)
	v_mfma_f32_16x16x32_bf16 v[114:117], v[206:209], v[150:153], v[114:117]
	v_mfma_f32_16x16x32_bf16 v[102:105], v[182:185], v[158:161], v[102:105]
	v_mfma_f32_16x16x32_bf16 v[98:101], v[206:209], v[158:161], v[98:101]
	v_mfma_f32_16x16x32_bf16 v[86:89], v[182:185], v[166:169], v[86:89]
	v_mfma_f32_16x16x32_bf16 v[82:85], v[206:209], v[166:169], v[82:85]
	v_mfma_f32_16x16x32_bf16 v[70:73], v[182:185], v[174:177], v[70:73]
	v_mfma_f32_16x16x32_bf16 v[66:69], v[206:209], v[174:177], v[66:69]
	s_setprio 0
	s_mov_b32 m0, s15
	s_barrier
	ds_read_b128 v[146:149], v197 offset:16384
	ds_read_b128 v[150:153], v197 offset:17408
	ds_read_b128 v[154:157], v197 offset:18432
	ds_read_b128 v[158:161], v197 offset:19456
	ds_read_b128 v[162:165], v197 offset:20480
	ds_read_b128 v[166:169], v197 offset:21504
	ds_read_b128 v[170:173], v197 offset:22528
	ds_read_b128 v[174:177], v197 offset:23552
	buffer_load_dwordx4 v192, s[48:51], s78 offen lds
	s_add_i32 s33, s78, 0x20000
	s_mov_b32 m0, s18
	s_nop 0
	buffer_load_dwordx4 v192, s[48:51], s33 offen lds
	s_barrier
	s_waitcnt lgkmcnt(0)
	s_setprio 1
	s_waitcnt lgkmcnt(7)
	v_mfma_f32_16x16x32_bf16 v[62:65], v[130:133], v[146:149], v[62:65]
	v_mfma_f32_16x16x32_bf16 v[58:61], v[138:141], v[146:149], v[58:61]
	s_waitcnt lgkmcnt(5)
	v_mfma_f32_16x16x32_bf16 v[46:49], v[130:133], v[154:157], v[46:49]
	v_mfma_f32_16x16x32_bf16 v[42:45], v[138:141], v[154:157], v[42:45]
	s_waitcnt lgkmcnt(3)
	v_mfma_f32_16x16x32_bf16 v[30:33], v[130:133], v[162:165], v[30:33]
	v_mfma_f32_16x16x32_bf16 v[26:29], v[138:141], v[162:165], v[26:29]
	s_waitcnt lgkmcnt(1)
	v_mfma_f32_16x16x32_bf16 v[14:17], v[130:133], v[170:173], v[14:17]
	v_mfma_f32_16x16x32_bf16 v[10:13], v[138:141], v[170:173], v[10:13]
	v_mfma_f32_16x16x32_bf16 v[62:65], v[134:137], v[150:153], v[62:65]
	v_mfma_f32_16x16x32_bf16 v[58:61], v[142:145], v[150:153], v[58:61]
	v_mfma_f32_16x16x32_bf16 v[46:49], v[134:137], v[158:161], v[46:49]
	v_mfma_f32_16x16x32_bf16 v[42:45], v[142:145], v[158:161], v[42:45]
	v_mfma_f32_16x16x32_bf16 v[30:33], v[134:137], v[166:169], v[30:33]
	v_mfma_f32_16x16x32_bf16 v[26:29], v[142:145], v[166:169], v[26:29]
	s_waitcnt lgkmcnt(0)
	v_mfma_f32_16x16x32_bf16 v[14:17], v[134:137], v[174:177], v[14:17]
	v_mfma_f32_16x16x32_bf16 v[10:13], v[142:145], v[174:177], v[10:13]
	s_setprio 0
	s_barrier
	s_mov_b32 m0, s19
	s_add_i32 s33, s73, 0x40000
	buffer_load_dwordx4 v193, s[8:11], s33 offen lds
	s_add_i32 s33, s73, 0x60000
	s_mov_b32 m0, s20
	s_nop 0
	buffer_load_dwordx4 v193, s[8:11], s33 offen lds
	s_cmp_eq_u32 s100, 0
	s_cbranch_scc1 .Lfw_14_a
	s_waitcnt vmcnt(16)
	s_mov_b32 s100, 0
	s_branch .Lfw_14_b

.LBB0_3099:
	v_mov_b32_e32 v218, 0xbd38aa3b
	v_mov_b32_e32 v219, 0xbd38aa3b
	v_mov_b32_e32 v220, 0x44800000
	v_mov_b32_e32 v221, 0x44800000
	v_lshl_add_u32 v222, s47, 8, v188
	v_lshl_or_b32 v224, s46, 7, v189
	s_nop 0
	v_lshl_add_u32 v222, v222, 10, v224
	s_mov_b32 s46, s38
	s_mov_b32 s47, s39
	s_mov_b32 s50, s45
	v_pk_mul_f32 v[226:227], v[174:175], v[218:219]
	v_pk_mul_f32 v[228:229], v[176:177], v[218:219]
	v_pk_mul_f32 v[230:231], v[166:167], v[218:219]
	v_pk_mul_f32 v[232:233], v[168:169], v[218:219]
	v_exp_f32_e32 v226, v226
	v_exp_f32_e32 v227, v227
	v_exp_f32_e32 v228, v228
	v_exp_f32_e32 v229, v229
	v_exp_f32_e32 v230, v230
	v_exp_f32_e32 v231, v231
	v_exp_f32_e32 v232, v232
	v_exp_f32_e32 v233, v233
	v_pk_fma_f32 v[226:227], v[226:227], v[220:221], v[220:221]
	v_pk_fma_f32 v[228:229], v[228:229], v[220:221], v[220:221]
	v_pk_fma_f32 v[230:231], v[230:231], v[220:221], v[220:221]
	v_pk_fma_f32 v[232:233], v[232:233], v[220:221], v[220:221]
	v_rcp_f32_e32 v226, v226
	v_rcp_f32_e32 v227, v227
	v_rcp_f32_e32 v228, v228
	v_rcp_f32_e32 v229, v229
	v_rcp_f32_e32 v230, v230
	v_rcp_f32_e32 v231, v231
	v_rcp_f32_e32 v232, v232
	v_rcp_f32_e32 v233, v233
	v_pk_mul_f32 v[174:175], v[174:175], v[170:171]
	v_pk_mul_f32 v[176:177], v[176:177], v[172:173]
	v_pk_mul_f32 v[166:167], v[166:167], v[162:163]
	v_pk_mul_f32 v[168:169], v[168:169], v[164:165]
	v_pk_mul_f32 v[174:175], v[174:175], v[226:227]
	v_pk_mul_f32 v[176:177], v[176:177], v[228:229]
	v_pk_mul_f32 v[166:167], v[166:167], v[230:231]
	v_pk_mul_f32 v[168:169], v[168:169], v[232:233]
	v_mov_b32_e32 v223, v222
	v_cvt_pk_fp8_f32 v234, v174, v175
	v_cvt_pk_fp8_f32 v235, v166, v167
	v_cvt_pk_fp8_f32 v234, v176, v177 op_sel:[0,0,1]
	v_cvt_pk_fp8_f32 v235, v168, v169 op_sel:[0,0,1]
	s_nop 0
	global_store_dwordx2 v223, v[234:235], s[70:71]
	s_mov_b32 s100, 1
	v_pk_mul_f32 v[226:227], v[158:159], v[218:219]
	v_pk_mul_f32 v[228:229], v[160:161], v[218:219]
	v_pk_mul_f32 v[230:231], v[150:151], v[218:219]
	v_pk_mul_f32 v[232:233], v[152:153], v[218:219]
	v_exp_f32_e32 v226, v226
	v_exp_f32_e32 v227, v227
	v_exp_f32_e32 v228, v228
	v_exp_f32_e32 v229, v229
	v_exp_f32_e32 v230, v230
	v_exp_f32_e32 v231, v231
	v_exp_f32_e32 v232, v232
	v_exp_f32_e32 v233, v233
	v_pk_fma_f32 v[226:227], v[226:227], v[220:221], v[220:221]
	v_pk_fma_f32 v[228:229], v[228:229], v[220:221], v[220:221]
	v_pk_fma_f32 v[230:231], v[230:231], v[220:221], v[220:221]
	v_pk_fma_f32 v[232:233], v[232:233], v[220:221], v[220:221]
	v_rcp_f32_e32 v226, v226
	v_rcp_f32_e32 v227, v227
	v_rcp_f32_e32 v228, v228
	v_rcp_f32_e32 v229, v229
	v_rcp_f32_e32 v230, v230
	v_rcp_f32_e32 v231, v231
	v_rcp_f32_e32 v232, v232
	v_rcp_f32_e32 v233, v233
	v_pk_mul_f32 v[158:159], v[158:159], v[154:155]
	v_pk_mul_f32 v[160:161], v[160:161], v[156:157]
	v_pk_mul_f32 v[150:151], v[150:151], v[146:147]
	v_pk_mul_f32 v[152:153], v[152:153], v[148:149]
	v_pk_mul_f32 v[158:159], v[158:159], v[226:227]
	v_pk_mul_f32 v[160:161], v[160:161], v[228:229]
	v_pk_mul_f32 v[150:151], v[150:151], v[230:231]
	v_pk_mul_f32 v[152:153], v[152:153], v[232:233]
	v_add_u32_e32 v225, 0x4000, v222
	v_cvt_pk_fp8_f32 v236, v158, v159
	v_cvt_pk_fp8_f32 v237, v150, v151
	v_cvt_pk_fp8_f32 v236, v160, v161 op_sel:[0,0,1]
	v_cvt_pk_fp8_f32 v237, v152, v153 op_sel:[0,0,1]
	s_nop 0
	global_store_dwordx2 v225, v[236:237], s[70:71]
	s_mov_b32 s100, 1
	v_pk_mul_f32 v[226:227], v[142:143], v[218:219]
	v_pk_mul_f32 v[228:229], v[144:145], v[218:219]
	v_pk_mul_f32 v[230:231], v[134:135], v[218:219]
	v_pk_mul_f32 v[232:233], v[136:137], v[218:219]
	v_exp_f32_e32 v226, v226
	v_exp_f32_e32 v227, v227
	v_exp_f32_e32 v228, v228
	v_exp_f32_e32 v229, v229
	v_exp_f32_e32 v230, v230
	v_exp_f32_e32 v231, v231
	v_exp_f32_e32 v232, v232
	v_exp_f32_e32 v233, v233
	v_pk_fma_f32 v[226:227], v[226:227], v[220:221], v[220:221]
	v_pk_fma_f32 v[228:229], v[228:229], v[220:221], v[220:221]
	v_pk_fma_f32 v[230:231], v[230:231], v[220:221], v[220:221]
	v_pk_fma_f32 v[232:233], v[232:233], v[220:221], v[220:221]
	v_rcp_f32_e32 v226, v226
	v_rcp_f32_e32 v227, v227
	v_rcp_f32_e32 v228, v228
	v_rcp_f32_e32 v229, v229
	v_rcp_f32_e32 v230, v230
	v_rcp_f32_e32 v231, v231
	v_rcp_f32_e32 v232, v232
	v_rcp_f32_e32 v233, v233
	v_pk_mul_f32 v[142:143], v[142:143], v[138:139]
	v_pk_mul_f32 v[144:145], v[144:145], v[140:141]
	v_pk_mul_f32 v[134:135], v[134:135], v[130:131]
	v_pk_mul_f32 v[136:137], v[136:137], v[132:133]
	v_pk_mul_f32 v[142:143], v[142:143], v[226:227]
	v_pk_mul_f32 v[144:145], v[144:145], v[228:229]
	v_pk_mul_f32 v[134:135], v[134:135], v[230:231]
	v_pk_mul_f32 v[136:137], v[136:137], v[232:233]
	v_add_u32_e32 v223, 0x8000, v222
	v_cvt_pk_fp8_f32 v234, v142, v143
	v_cvt_pk_fp8_f32 v235, v134, v135
	v_cvt_pk_fp8_f32 v234, v144, v145 op_sel:[0,0,1]
	v_cvt_pk_fp8_f32 v235, v136, v137 op_sel:[0,0,1]
	s_nop 0
	global_store_dwordx2 v223, v[234:235], s[70:71]
	s_mov_b32 s100, 1
	v_pk_mul_f32 v[226:227], v[126:127], v[218:219]
	v_pk_mul_f32 v[228:229], v[128:129], v[218:219]
	v_pk_mul_f32 v[230:231], v[118:119], v[218:219]
	v_pk_mul_f32 v[232:233], v[120:121], v[218:219]
	v_exp_f32_e32 v226, v226
	v_exp_f32_e32 v227, v227
	v_exp_f32_e32 v228, v228
	v_exp_f32_e32 v229, v229
	v_exp_f32_e32 v230, v230
	v_exp_f32_e32 v231, v231
	v_exp_f32_e32 v232, v232
	v_exp_f32_e32 v233, v233
	v_pk_fma_f32 v[226:227], v[226:227], v[220:221], v[220:221]
	v_pk_fma_f32 v[228:229], v[228:229], v[220:221], v[220:221]
	v_pk_fma_f32 v[230:231], v[230:231], v[220:221], v[220:221]
	v_pk_fma_f32 v[232:233], v[232:233], v[220:221], v[220:221]
	v_rcp_f32_e32 v226, v226
	v_rcp_f32_e32 v227, v227
	v_rcp_f32_e32 v228, v228
	v_rcp_f32_e32 v229, v229
	v_rcp_f32_e32 v230, v230
	v_rcp_f32_e32 v231, v231
	v_rcp_f32_e32 v232, v232
	v_rcp_f32_e32 v233, v233
	v_pk_mul_f32 v[126:127], v[126:127], v[122:123]
	v_pk_mul_f32 v[128:129], v[128:129], v[124:125]
	v_pk_mul_f32 v[118:119], v[118:119], v[114:115]
	v_pk_mul_f32 v[120:121], v[120:121], v[116:117]
	v_pk_mul_f32 v[126:127], v[126:127], v[226:227]
	v_pk_mul_f32 v[128:129], v[128:129], v[228:229]
	v_pk_mul_f32 v[118:119], v[118:119], v[230:231]
	v_pk_mul_f32 v[120:121], v[120:121], v[232:233]
	v_add_u32_e32 v225, 0xc000, v222
	v_cvt_pk_fp8_f32 v236, v126, v127
	v_cvt_pk_fp8_f32 v237, v118, v119
	v_cvt_pk_fp8_f32 v236, v128, v129 op_sel:[0,0,1]
	v_cvt_pk_fp8_f32 v237, v120, v121 op_sel:[0,0,1]
	s_nop 0
	global_store_dwordx2 v225, v[236:237], s[70:71]
	s_mov_b32 s100, 1
	v_pk_mul_f32 v[226:227], v[110:111], v[218:219]
	v_pk_mul_f32 v[228:229], v[112:113], v[218:219]
	v_pk_mul_f32 v[230:231], v[102:103], v[218:219]
	v_pk_mul_f32 v[232:233], v[104:105], v[218:219]
	v_exp_f32_e32 v226, v226
	v_exp_f32_e32 v227, v227
	v_exp_f32_e32 v228, v228
	v_exp_f32_e32 v229, v229
	v_exp_f32_e32 v230, v230
	v_exp_f32_e32 v231, v231
	v_exp_f32_e32 v232, v232
	v_exp_f32_e32 v233, v233
	v_pk_fma_f32 v[226:227], v[226:227], v[220:221], v[220:221]
	v_pk_fma_f32 v[228:229], v[228:229], v[220:221], v[220:221]
	v_pk_fma_f32 v[230:231], v[230:231], v[220:221], v[220:221]
	v_pk_fma_f32 v[232:233], v[232:233], v[220:221], v[220:221]
	v_rcp_f32_e32 v226, v226
	v_rcp_f32_e32 v227, v227
	v_rcp_f32_e32 v228, v228
	v_rcp_f32_e32 v229, v229
	v_rcp_f32_e32 v230, v230
	v_rcp_f32_e32 v231, v231
	v_rcp_f32_e32 v232, v232
	v_rcp_f32_e32 v233, v233
	v_pk_mul_f32 v[110:111], v[110:111], v[106:107]
	v_pk_mul_f32 v[112:113], v[112:113], v[108:109]
	v_pk_mul_f32 v[102:103], v[102:103], v[98:99]
	v_pk_mul_f32 v[104:105], v[104:105], v[100:101]
	v_pk_mul_f32 v[110:111], v[110:111], v[226:227]
	v_pk_mul_f32 v[112:113], v[112:113], v[228:229]
	v_pk_mul_f32 v[102:103], v[102:103], v[230:231]
	v_pk_mul_f32 v[104:105], v[104:105], v[232:233]
	v_add_u32_e32 v223, 0x20000, v222
	v_cvt_pk_fp8_f32 v234, v110, v111
	v_cvt_pk_fp8_f32 v235, v102, v103
	v_cvt_pk_fp8_f32 v234, v112, v113 op_sel:[0,0,1]
	v_cvt_pk_fp8_f32 v235, v104, v105 op_sel:[0,0,1]
	s_nop 0
	global_store_dwordx2 v223, v[234:235], s[70:71]
	s_mov_b32 s100, 1
	v_pk_mul_f32 v[226:227], v[94:95], v[218:219]
	v_pk_mul_f32 v[228:229], v[96:97], v[218:219]
	v_pk_mul_f32 v[230:231], v[86:87], v[218:219]
	v_pk_mul_f32 v[232:233], v[88:89], v[218:219]
	v_exp_f32_e32 v226, v226
	v_exp_f32_e32 v227, v227
	v_exp_f32_e32 v228, v228
	v_exp_f32_e32 v229, v229
	v_exp_f32_e32 v230, v230
	v_exp_f32_e32 v231, v231
	v_exp_f32_e32 v232, v232
	v_exp_f32_e32 v233, v233
	v_pk_fma_f32 v[226:227], v[226:227], v[220:221], v[220:221]
	v_pk_fma_f32 v[228:229], v[228:229], v[220:221], v[220:221]
	v_pk_fma_f32 v[230:231], v[230:231], v[220:221], v[220:221]
	v_pk_fma_f32 v[232:233], v[232:233], v[220:221], v[220:221]
	v_rcp_f32_e32 v226, v226
	v_rcp_f32_e32 v227, v227
	v_rcp_f32_e32 v228, v228
	v_rcp_f32_e32 v229, v229
	v_rcp_f32_e32 v230, v230
	v_rcp_f32_e32 v231, v231
	v_rcp_f32_e32 v232, v232
	v_rcp_f32_e32 v233, v233
	v_pk_mul_f32 v[94:95], v[94:95], v[90:91]
	v_pk_mul_f32 v[96:97], v[96:97], v[92:93]
	v_pk_mul_f32 v[86:87], v[86:87], v[82:83]
	v_pk_mul_f32 v[88:89], v[88:89], v[84:85]
	v_pk_mul_f32 v[94:95], v[94:95], v[226:227]
	v_pk_mul_f32 v[96:97], v[96:97], v[228:229]
	v_pk_mul_f32 v[86:87], v[86:87], v[230:231]
	v_pk_mul_f32 v[88:89], v[88:89], v[232:233]
	v_add_u32_e32 v225, 0x24000, v222
	v_cvt_pk_fp8_f32 v236, v94, v95
	v_cvt_pk_fp8_f32 v237, v86, v87
	v_cvt_pk_fp8_f32 v236, v96, v97 op_sel:[0,0,1]
	v_cvt_pk_fp8_f32 v237, v88, v89 op_sel:[0,0,1]
	s_nop 0
	global_store_dwordx2 v225, v[236:237], s[70:71]
	s_mov_b32 s100, 1
	v_pk_mul_f32 v[226:227], v[78:79], v[218:219]
	v_pk_mul_f32 v[228:229], v[80:81], v[218:219]
	v_pk_mul_f32 v[230:231], v[70:71], v[218:219]
	v_pk_mul_f32 v[232:233], v[72:73], v[218:219]
	v_exp_f32_e32 v226, v226
	v_exp_f32_e32 v227, v227
	v_exp_f32_e32 v228, v228
	v_exp_f32_e32 v229, v229
	v_exp_f32_e32 v230, v230
	v_exp_f32_e32 v231, v231
	v_exp_f32_e32 v232, v232
	v_exp_f32_e32 v233, v233
	v_pk_fma_f32 v[226:227], v[226:227], v[220:221], v[220:221]
	v_pk_fma_f32 v[228:229], v[228:229], v[220:221], v[220:221]
	v_pk_fma_f32 v[230:231], v[230:231], v[220:221], v[220:221]
	v_pk_fma_f32 v[232:233], v[232:233], v[220:221], v[220:221]
	v_rcp_f32_e32 v226, v226
	v_rcp_f32_e32 v227, v227
	v_rcp_f32_e32 v228, v228
	v_rcp_f32_e32 v229, v229
	v_rcp_f32_e32 v230, v230
	v_rcp_f32_e32 v231, v231
	v_rcp_f32_e32 v232, v232
	v_rcp_f32_e32 v233, v233
	v_pk_mul_f32 v[78:79], v[78:79], v[74:75]
	v_pk_mul_f32 v[80:81], v[80:81], v[76:77]
	v_pk_mul_f32 v[70:71], v[70:71], v[66:67]
	v_pk_mul_f32 v[72:73], v[72:73], v[68:69]
	v_pk_mul_f32 v[78:79], v[78:79], v[226:227]
	v_pk_mul_f32 v[80:81], v[80:81], v[228:229]
	v_pk_mul_f32 v[70:71], v[70:71], v[230:231]
	v_pk_mul_f32 v[72:73], v[72:73], v[232:233]
	v_add_u32_e32 v223, 0x28000, v222
	v_cvt_pk_fp8_f32 v234, v78, v79
	v_cvt_pk_fp8_f32 v235, v70, v71
	v_cvt_pk_fp8_f32 v234, v80, v81 op_sel:[0,0,1]
	v_cvt_pk_fp8_f32 v235, v72, v73 op_sel:[0,0,1]
	s_nop 0
	global_store_dwordx2 v223, v[234:235], s[70:71]
	s_mov_b32 s100, 1
	v_pk_mul_f32 v[226:227], v[62:63], v[218:219]
	v_pk_mul_f32 v[228:229], v[64:65], v[218:219]
	v_pk_mul_f32 v[230:231], v[54:55], v[218:219]
	v_pk_mul_f32 v[232:233], v[56:57], v[218:219]
	v_exp_f32_e32 v226, v226
	v_exp_f32_e32 v227, v227
	v_exp_f32_e32 v228, v228
	v_exp_f32_e32 v229, v229
	v_exp_f32_e32 v230, v230
	v_exp_f32_e32 v231, v231
	v_exp_f32_e32 v232, v232
	v_exp_f32_e32 v233, v233
	v_pk_fma_f32 v[226:227], v[226:227], v[220:221], v[220:221]
	v_pk_fma_f32 v[228:229], v[228:229], v[220:221], v[220:221]
	v_pk_fma_f32 v[230:231], v[230:231], v[220:221], v[220:221]
	v_pk_fma_f32 v[232:233], v[232:233], v[220:221], v[220:221]
	v_rcp_f32_e32 v226, v226
	v_rcp_f32_e32 v227, v227
	v_rcp_f32_e32 v228, v228
	v_rcp_f32_e32 v229, v229
	v_rcp_f32_e32 v230, v230
	v_rcp_f32_e32 v231, v231
	v_rcp_f32_e32 v232, v232
	v_rcp_f32_e32 v233, v233
	v_pk_mul_f32 v[62:63], v[62:63], v[58:59]
	v_pk_mul_f32 v[64:65], v[64:65], v[60:61]
	v_pk_mul_f32 v[54:55], v[54:55], v[50:51]
	v_pk_mul_f32 v[56:57], v[56:57], v[52:53]
	v_pk_mul_f32 v[62:63], v[62:63], v[226:227]
	v_pk_mul_f32 v[64:65], v[64:65], v[228:229]
	v_pk_mul_f32 v[54:55], v[54:55], v[230:231]
	v_pk_mul_f32 v[56:57], v[56:57], v[232:233]
	v_add_u32_e32 v225, 0x2c000, v222
	v_cvt_pk_fp8_f32 v236, v62, v63
	v_cvt_pk_fp8_f32 v237, v54, v55
	v_cvt_pk_fp8_f32 v236, v64, v65 op_sel:[0,0,1]
	v_cvt_pk_fp8_f32 v237, v56, v57 op_sel:[0,0,1]
	s_nop 0
	global_store_dwordx2 v225, v[236:237], s[70:71]
	s_mov_b32 s100, 1
	s_and_b64 vcc, exec, s[4:5]
	s_cbranch_vccnz .LBB0_3114

.LBB0_3185:
	ds_read_b128 v[144:147], v138
	ds_read_b128 v[148:151], v138 offset:1024
	ds_read_b128 v[152:155], v138 offset:2048
	ds_read_b128 v[156:159], v138 offset:3072
	s_add_i32 s10, s7, 0xfffd0080
	s_cmp_eq_u32 s72, 4
	s_cselect_b32 s74, s6, s10
	s_cselect_b32 s73, s57, s71
	s_or_b32 s75, s74, 0x80
	s_add_i32 s10, s7, 0xffff0000
	s_mov_b32 m0, s38
	ds_read_b128 v[160:163], v139
	ds_read_b128 v[164:167], v139 offset:1024
	ds_read_b128 v[168:171], v139 offset:2048
	ds_read_b128 v[172:175], v139 offset:3072
	ds_read_b128 v[176:179], v139 offset:4096
	ds_read_b128 v[180:183], v139 offset:5120
	ds_read_b128 v[184:187], v139 offset:6144
	ds_read_b128 v[188:191], v139 offset:7168
	buffer_load_dwordx4 v134, s[44:47], s10 offen lds
	s_mov_b32 m0, s39
	s_nop 0
	buffer_load_dwordx4 v134, s[44:47], s7 offen lds
	s_waitcnt lgkmcnt(8)
	s_barrier
	s_waitcnt lgkmcnt(0)
	s_setprio 1
	s_waitcnt lgkmcnt(4)
	v_mfma_f32_16x16x128_f8f6f4 v[114:117], v[144:151], v[168:175], v[114:117]
	v_mfma_f32_16x16x128_f8f6f4 v[106:109], v[152:159], v[168:175], v[106:109]
	s_waitcnt lgkmcnt(2)
	v_mfma_f32_16x16x128_f8f6f4 v[98:101], v[144:151], v[176:183], v[98:101]
	v_mfma_f32_16x16x128_f8f6f4 v[200:203], v[144:151], v[160:167], v[126:129]
	v_mfma_f32_16x16x128_f8f6f4 v[204:207], v[152:159], v[160:167], v[122:125]
	v_mfma_f32_16x16x128_f8f6f4 v[208:211], v[152:159], v[176:183], v[90:93]
	s_waitcnt lgkmcnt(0)
	v_mfma_f32_16x16x128_f8f6f4 v[212:215], v[144:151], v[184:191], v[82:85]
	v_mfma_f32_16x16x128_f8f6f4 v[216:219], v[152:159], v[184:191], v[74:77]
	s_setprio 0
	s_barrier
	s_mov_b32 m0, s22
	s_mov_b32 s10, s46
	s_mov_b32 s11, s47
	ds_read_b128 v[122:125], v254
	ds_read_b128 v[126:129], v254 offset:1024
	ds_read_b128 v[192:195], v254 offset:2048
	ds_read_b128 v[196:199], v254 offset:3072
	buffer_load_dwordx4 v135, s[8:11], s73 offen lds
	s_add_i32 s33, s73, 0x10000
	s_mov_b32 m0, s23
	s_nop 0
	buffer_load_dwordx4 v135, s[8:11], s33 offen lds
	s_barrier
	s_waitcnt lgkmcnt(0)
	s_setprio 1
	s_waitcnt lgkmcnt(2)
	v_mfma_f32_16x16x128_f8f6f4 v[118:121], v[122:129], v[160:167], v[118:121]
	s_waitcnt lgkmcnt(0)
	v_mfma_f32_16x16x128_f8f6f4 v[110:113], v[192:199], v[160:167], v[110:113]
	v_mfma_f32_16x16x128_f8f6f4 v[102:105], v[122:129], v[168:175], v[102:105]
	v_mfma_f32_16x16x128_f8f6f4 v[160:163], v[192:199], v[168:175], v[94:97]
	v_mfma_f32_16x16x128_f8f6f4 v[164:167], v[122:129], v[176:183], v[86:89]
	v_mfma_f32_16x16x128_f8f6f4 v[168:171], v[192:199], v[176:183], v[78:81]
	v_mfma_f32_16x16x128_f8f6f4 v[172:175], v[122:129], v[184:191], v[70:73]
	v_mfma_f32_16x16x128_f8f6f4 v[176:179], v[192:199], v[184:191], v[18:21]
	s_setprio 0
	s_mov_b32 m0, s21
	s_barrier
	ds_read_b128 v[66:69], v139 offset:16384
	s_nop 1
	ds_read_b128 v[70:73], v139 offset:17408
	ds_read_b128 v[74:77], v139 offset:18432
	ds_read_b128 v[78:81], v139 offset:19456
	ds_read_b128 v[82:85], v139 offset:20480
	ds_read_b128 v[86:89], v139 offset:21504
	ds_read_b128 v[90:93], v139 offset:22528
	ds_read_b128 v[94:97], v139 offset:23552
	buffer_load_dwordx4 v134, s[44:47], s74 offen lds
	s_add_i32 s33, s74, 0x10000
	s_mov_b32 m0, s24
	s_nop 0
	buffer_load_dwordx4 v134, s[44:47], s33 offen lds
	s_barrier
	s_waitcnt lgkmcnt(0)
	s_setprio 1
	s_waitcnt lgkmcnt(6)
	v_mfma_f32_16x16x128_f8f6f4 v[62:65], v[144:151], v[66:73], v[62:65]
	v_mfma_f32_16x16x128_f8f6f4 v[58:61], v[152:159], v[66:73], v[58:61]
	s_waitcnt lgkmcnt(4)
	v_mfma_f32_16x16x128_f8f6f4 v[50:53], v[144:151], v[74:81], v[50:53]
	s_waitcnt lgkmcnt(0)
	v_mfma_f32_16x16x128_f8f6f4 v[232:235], v[144:151], v[90:97], v[232:235]
	v_mfma_f32_16x16x128_f8f6f4 v[220:223], v[152:159], v[74:81], v[42:45]
	v_mfma_f32_16x16x128_f8f6f4 v[224:227], v[144:151], v[82:89], v[34:37]
	v_mfma_f32_16x16x128_f8f6f4 v[228:231], v[152:159], v[82:89], v[26:29]
	v_mfma_f32_16x16x128_f8f6f4 v[236:239], v[152:159], v[90:97], v[10:13]
	s_setprio 0
	s_barrier
	s_mov_b32 m0, s25
	s_add_i32 s33, s73, 0x20000
	buffer_load_dwordx4 v135, s[8:11], s33 offen lds
	s_add_i32 s33, s73, 0x30000
	s_mov_b32 m0, s26
	s_nop 0
	buffer_load_dwordx4 v135, s[8:11], s33 offen lds
	s_cmp_eq_u32 s100, 0
	s_cbranch_scc1 .Lfw_16_a
	s_waitcnt vmcnt(16)
	s_mov_b32 s100, 0
	s_branch .Lfw_16_b
